# v10 + split-K slab reduction of context rows re-emitted as a 3-deep stream of 4-load units (was 18-24 dependent round trips)
# baseline (speedup 1.0000x reference)
.LBB0_771:
	s_add_i32 s14, s4, s94
	s_cmpk_lt_i32 s14, 0x4200
	s_cselect_b64 s[8:9], -1, 0
	s_and_b64 s[0:1], s[8:9], exec
	s_cselect_b32 s6, s14, s4
	s_ashr_i32 s7, s6, 31
	s_lshl_b64 s[0:1], s[6:7], 12
	v_lshl_add_u64 v[32:33], v[80:81], 0, s[0:1]
	s_waitcnt vmcnt(0)
	global_load_dwordx4 v[62:65], v[32:33], off
	global_load_dwordx4 v[58:61], v[32:33], off offset:1024
	global_load_dwordx4 v[54:57], v[32:33], off offset:2048
	global_load_dwordx4 v[50:53], v[32:33], off offset:3072
	v_cvt_f32_f16_sdwa v167, v46 dst_sel:DWORD dst_unused:UNUSED_PAD src0_sel:WORD_1
	v_cvt_f32_f16_e32 v166, v46
	v_cvt_f32_f16_sdwa v163, v47 dst_sel:DWORD dst_unused:UNUSED_PAD src0_sel:WORD_1
	v_cvt_f32_f16_e32 v162, v47
	v_cvt_f32_f16_sdwa v161, v48 dst_sel:DWORD dst_unused:UNUSED_PAD src0_sel:WORD_1
	v_cvt_f32_f16_e32 v160, v48
	v_cvt_f32_f16_sdwa v165, v49 dst_sel:DWORD dst_unused:UNUSED_PAD src0_sel:WORD_1
	v_cvt_f32_f16_e32 v164, v49
	v_cvt_f32_f16_sdwa v155, v42 dst_sel:DWORD dst_unused:UNUSED_PAD src0_sel:WORD_1
	v_cvt_f32_f16_e32 v154, v42
	v_cvt_f32_f16_sdwa v157, v43 dst_sel:DWORD dst_unused:UNUSED_PAD src0_sel:WORD_1
	v_cvt_f32_f16_e32 v156, v43
	v_cvt_f32_f16_sdwa v153, v44 dst_sel:DWORD dst_unused:UNUSED_PAD src0_sel:WORD_1
	v_cvt_f32_f16_e32 v152, v44
	v_cvt_f32_f16_sdwa v159, v45 dst_sel:DWORD dst_unused:UNUSED_PAD src0_sel:WORD_1
	v_cvt_f32_f16_e32 v158, v45
	v_cvt_f32_f16_sdwa v45, v38 dst_sel:DWORD dst_unused:UNUSED_PAD src0_sel:WORD_1
	v_cvt_f32_f16_e32 v44, v38
	v_cvt_f32_f16_sdwa v47, v39 dst_sel:DWORD dst_unused:UNUSED_PAD src0_sel:WORD_1
	v_cvt_f32_f16_e32 v46, v39
	v_cvt_f32_f16_sdwa v43, v40 dst_sel:DWORD dst_unused:UNUSED_PAD src0_sel:WORD_1
	v_cvt_f32_f16_e32 v42, v40
	v_cvt_f32_f16_sdwa v49, v41 dst_sel:DWORD dst_unused:UNUSED_PAD src0_sel:WORD_1
	v_cvt_f32_f16_e32 v48, v41
	v_cvt_f32_f16_sdwa v39, v34 dst_sel:DWORD dst_unused:UNUSED_PAD src0_sel:WORD_1
	v_cvt_f32_f16_e32 v38, v34
	v_cvt_f32_f16_sdwa v41, v35 dst_sel:DWORD dst_unused:UNUSED_PAD src0_sel:WORD_1
	v_cvt_f32_f16_e32 v40, v35
	v_cvt_f32_f16_sdwa v33, v36 dst_sel:DWORD dst_unused:UNUSED_PAD src0_sel:WORD_1
	v_cvt_f32_f16_e32 v32, v36
	v_cvt_f32_f16_sdwa v35, v37 dst_sel:DWORD dst_unused:UNUSED_PAD src0_sel:WORD_1
	v_cvt_f32_f16_e32 v34, v37
	s_cmpk_gt_i32 s4, 0x3fff
	s_cselect_b64 s[2:3], -1, 0
	s_cmpk_lt_i32 s4, 0x4000
	s_cbranch_scc1 .LBB0_773
	s_add_i32 s86, s4, 0xffffc000
	s_lshl_b64 s[0:1], s[86:87], 13
	v_lshl_add_u64 v[36:37], v[82:83], 0, s[0:1]
	global_load_dwordx4 v[190:193], v[36:37], off
	global_load_dwordx4 v[194:197], v[36:37], off offset:16
	global_load_dwordx4 v[198:201], v[36:37], off offset:2048
	global_load_dwordx4 v[204:207], v[36:37], off offset:2064
	s_mov_b64 s[0:1], 0x400000
	v_lshl_add_u64 v[232:233], v[36:37], 0, s[0:1]
	global_load_dwordx4 v[208:211], v[232:233], off
	global_load_dwordx4 v[212:215], v[232:233], off offset:16
	global_load_dwordx4 v[216:219], v[232:233], off offset:2048
	global_load_dwordx4 v[220:223], v[232:233], off offset:2064
	s_mov_b64 s[0:1], 0x800000
	v_lshl_add_u64 v[232:233], v[36:37], 0, s[0:1]
	global_load_dwordx4 v[224:227], v[232:233], off
	global_load_dwordx4 v[228:231], v[232:233], off offset:16
	global_load_dwordx4 v[238:241], v[232:233], off offset:2048
	global_load_dwordx4 v[242:245], v[232:233], off offset:2064
	s_waitcnt vmcnt(8)
	v_mov_b64_e32 v[174:175], v[190:191]
	v_mov_b64_e32 v[176:177], v[192:193]
	v_mov_b64_e32 v[178:179], v[194:195]
	v_mov_b64_e32 v[180:181], v[196:197]
	v_mov_b64_e32 v[182:183], v[198:199]
	v_mov_b64_e32 v[184:185], v[200:201]
	v_mov_b64_e32 v[186:187], v[204:205]
	v_mov_b64_e32 v[188:189], v[206:207]
	s_mov_b64 s[0:1], 0xc00000
	v_lshl_add_u64 v[232:233], v[36:37], 0, s[0:1]
	global_load_dwordx4 v[190:193], v[232:233], off
	global_load_dwordx4 v[194:197], v[232:233], off offset:16
	global_load_dwordx4 v[198:201], v[232:233], off offset:2048
	global_load_dwordx4 v[204:207], v[232:233], off offset:2064
	s_waitcnt vmcnt(8)
	v_pk_add_f32 v[174:175], v[174:175], v[208:209]
	v_pk_add_f32 v[176:177], v[176:177], v[210:211]
	v_pk_add_f32 v[178:179], v[178:179], v[212:213]
	v_pk_add_f32 v[180:181], v[180:181], v[214:215]
	v_pk_add_f32 v[182:183], v[182:183], v[216:217]
	v_pk_add_f32 v[184:185], v[184:185], v[218:219]
	v_pk_add_f32 v[186:187], v[186:187], v[220:221]
	v_pk_add_f32 v[188:189], v[188:189], v[222:223]
	s_mov_b64 s[0:1], 0x1000000
	v_lshl_add_u64 v[232:233], v[36:37], 0, s[0:1]
	global_load_dwordx4 v[208:211], v[232:233], off
	global_load_dwordx4 v[212:215], v[232:233], off offset:16
	global_load_dwordx4 v[216:219], v[232:233], off offset:2048
	global_load_dwordx4 v[220:223], v[232:233], off offset:2064
	s_waitcnt vmcnt(8)
	v_pk_add_f32 v[174:175], v[174:175], v[224:225]
	v_pk_add_f32 v[176:177], v[176:177], v[226:227]
	v_pk_add_f32 v[178:179], v[178:179], v[228:229]
	v_pk_add_f32 v[180:181], v[180:181], v[230:231]
	v_pk_add_f32 v[182:183], v[182:183], v[238:239]
	v_pk_add_f32 v[184:185], v[184:185], v[240:241]
	v_pk_add_f32 v[186:187], v[186:187], v[242:243]
	v_pk_add_f32 v[188:189], v[188:189], v[244:245]
	s_mov_b64 s[0:1], 0x1400000
	v_lshl_add_u64 v[232:233], v[36:37], 0, s[0:1]
	global_load_dwordx4 v[224:227], v[232:233], off
	global_load_dwordx4 v[228:231], v[232:233], off offset:16
	global_load_dwordx4 v[238:241], v[232:233], off offset:2048
	global_load_dwordx4 v[242:245], v[232:233], off offset:2064
	s_waitcnt vmcnt(8)
	v_pk_add_f32 v[174:175], v[174:175], v[190:191]
	v_pk_add_f32 v[176:177], v[176:177], v[192:193]
	v_pk_add_f32 v[178:179], v[178:179], v[194:195]
	v_pk_add_f32 v[180:181], v[180:181], v[196:197]
	v_pk_add_f32 v[182:183], v[182:183], v[198:199]
	v_pk_add_f32 v[184:185], v[184:185], v[200:201]
	v_pk_add_f32 v[186:187], v[186:187], v[204:205]
	v_pk_add_f32 v[188:189], v[188:189], v[206:207]
	s_mov_b64 s[0:1], 0x1800000
	v_lshl_add_u64 v[232:233], v[36:37], 0, s[0:1]
	global_load_dwordx4 v[190:193], v[232:233], off
	global_load_dwordx4 v[194:197], v[232:233], off offset:16
	global_load_dwordx4 v[198:201], v[232:233], off offset:2048
	global_load_dwordx4 v[204:207], v[232:233], off offset:2064
	s_waitcnt vmcnt(8)
	v_pk_add_f32 v[174:175], v[174:175], v[208:209]
	v_pk_add_f32 v[176:177], v[176:177], v[210:211]
	v_pk_add_f32 v[178:179], v[178:179], v[212:213]
	v_pk_add_f32 v[180:181], v[180:181], v[214:215]
	v_pk_add_f32 v[182:183], v[182:183], v[216:217]
	v_pk_add_f32 v[184:185], v[184:185], v[218:219]
	v_pk_add_f32 v[186:187], v[186:187], v[220:221]
	v_pk_add_f32 v[188:189], v[188:189], v[222:223]
	s_mov_b64 s[0:1], 0x1c00000
	v_lshl_add_u64 v[232:233], v[36:37], 0, s[0:1]
	global_load_dwordx4 v[208:211], v[232:233], off
	global_load_dwordx4 v[212:215], v[232:233], off offset:16
	global_load_dwordx4 v[216:219], v[232:233], off offset:2048
	global_load_dwordx4 v[220:223], v[232:233], off offset:2064
	s_waitcnt vmcnt(8)
	v_pk_add_f32 v[174:175], v[174:175], v[224:225]
	v_pk_add_f32 v[176:177], v[176:177], v[226:227]
	v_pk_add_f32 v[178:179], v[178:179], v[228:229]
	v_pk_add_f32 v[180:181], v[180:181], v[230:231]
	v_pk_add_f32 v[182:183], v[182:183], v[238:239]
	v_pk_add_f32 v[184:185], v[184:185], v[240:241]
	v_pk_add_f32 v[186:187], v[186:187], v[242:243]
	v_pk_add_f32 v[188:189], v[188:189], v[244:245]
	global_load_dwordx4 v[224:227], v[74:75], off
	global_load_dwordx4 v[228:231], v[74:75], off offset:16
	global_load_dwordx4 v[238:241], v[74:75], off offset:2048
	global_load_dwordx4 v[242:245], v[74:75], off offset:2064
	s_waitcnt vmcnt(8)
	v_pk_add_f32 v[174:175], v[174:175], v[190:191]
	v_pk_add_f32 v[176:177], v[176:177], v[192:193]
	v_pk_add_f32 v[178:179], v[178:179], v[194:195]
	v_pk_add_f32 v[180:181], v[180:181], v[196:197]
	v_pk_add_f32 v[182:183], v[182:183], v[198:199]
	v_pk_add_f32 v[184:185], v[184:185], v[200:201]
	v_pk_add_f32 v[186:187], v[186:187], v[204:205]
	v_pk_add_f32 v[188:189], v[188:189], v[206:207]
	s_mov_b64 s[0:1], 0x1000
	v_lshl_add_u64 v[232:233], v[36:37], 0, s[0:1]
	global_load_dwordx4 v[190:193], v[232:233], off
	global_load_dwordx4 v[194:197], v[232:233], off offset:16
	global_load_dwordx4 v[198:201], v[232:233], off offset:2048
	global_load_dwordx4 v[204:207], v[232:233], off offset:2064
	s_waitcnt vmcnt(8)
	v_pk_add_f32 v[174:175], v[174:175], v[208:209]
	v_pk_add_f32 v[176:177], v[176:177], v[210:211]
	v_pk_add_f32 v[178:179], v[178:179], v[212:213]
	v_pk_add_f32 v[180:181], v[180:181], v[214:215]
	v_pk_add_f32 v[182:183], v[182:183], v[216:217]
	v_pk_add_f32 v[184:185], v[184:185], v[218:219]
	v_pk_add_f32 v[186:187], v[186:187], v[220:221]
	v_pk_add_f32 v[188:189], v[188:189], v[222:223]
	s_mov_b64 s[0:1], 0x401000
	v_lshl_add_u64 v[232:233], v[36:37], 0, s[0:1]
	global_load_dwordx4 v[208:211], v[232:233], off
	global_load_dwordx4 v[212:215], v[232:233], off offset:16
	global_load_dwordx4 v[216:219], v[232:233], off offset:2048
	global_load_dwordx4 v[220:223], v[232:233], off offset:2064
	s_waitcnt vmcnt(8)
	v_pk_fma_f32 v[166:167], v[174:175], v[224:225], v[166:167]
	v_pk_fma_f32 v[162:163], v[176:177], v[226:227], v[162:163]
	v_pk_fma_f32 v[160:161], v[178:179], v[228:229], v[160:161]
	v_pk_fma_f32 v[164:165], v[180:181], v[230:231], v[164:165]
	v_pk_fma_f32 v[154:155], v[182:183], v[238:239], v[154:155]
	v_pk_fma_f32 v[156:157], v[184:185], v[240:241], v[156:157]
	v_pk_fma_f32 v[152:153], v[186:187], v[242:243], v[152:153]
	v_pk_fma_f32 v[158:159], v[188:189], v[244:245], v[158:159]
	s_mov_b64 s[0:1], 0x801000
	v_lshl_add_u64 v[232:233], v[36:37], 0, s[0:1]
	global_load_dwordx4 v[224:227], v[232:233], off
	global_load_dwordx4 v[228:231], v[232:233], off offset:16
	global_load_dwordx4 v[238:241], v[232:233], off offset:2048
	global_load_dwordx4 v[242:245], v[232:233], off offset:2064
	s_waitcnt vmcnt(8)
	v_mov_b64_e32 v[174:175], v[190:191]
	v_mov_b64_e32 v[176:177], v[192:193]
	v_mov_b64_e32 v[178:179], v[194:195]
	v_mov_b64_e32 v[180:181], v[196:197]
	v_mov_b64_e32 v[182:183], v[198:199]
	v_mov_b64_e32 v[184:185], v[200:201]
	v_mov_b64_e32 v[186:187], v[204:205]
	v_mov_b64_e32 v[188:189], v[206:207]
	s_mov_b64 s[0:1], 0xc01000
	v_lshl_add_u64 v[232:233], v[36:37], 0, s[0:1]
	global_load_dwordx4 v[190:193], v[232:233], off
	global_load_dwordx4 v[194:197], v[232:233], off offset:16
	global_load_dwordx4 v[198:201], v[232:233], off offset:2048
	global_load_dwordx4 v[204:207], v[232:233], off offset:2064
	s_waitcnt vmcnt(8)
	v_pk_add_f32 v[174:175], v[174:175], v[208:209]
	v_pk_add_f32 v[176:177], v[176:177], v[210:211]
	v_pk_add_f32 v[178:179], v[178:179], v[212:213]
	v_pk_add_f32 v[180:181], v[180:181], v[214:215]
	v_pk_add_f32 v[182:183], v[182:183], v[216:217]
	v_pk_add_f32 v[184:185], v[184:185], v[218:219]
	v_pk_add_f32 v[186:187], v[186:187], v[220:221]
	v_pk_add_f32 v[188:189], v[188:189], v[222:223]
	s_mov_b64 s[0:1], 0x1001000
	v_lshl_add_u64 v[232:233], v[36:37], 0, s[0:1]
	global_load_dwordx4 v[208:211], v[232:233], off
	global_load_dwordx4 v[212:215], v[232:233], off offset:16
	global_load_dwordx4 v[216:219], v[232:233], off offset:2048
	global_load_dwordx4 v[220:223], v[232:233], off offset:2064
	s_waitcnt vmcnt(8)
	v_pk_add_f32 v[174:175], v[174:175], v[224:225]
	v_pk_add_f32 v[176:177], v[176:177], v[226:227]
	v_pk_add_f32 v[178:179], v[178:179], v[228:229]
	v_pk_add_f32 v[180:181], v[180:181], v[230:231]
	v_pk_add_f32 v[182:183], v[182:183], v[238:239]
	v_pk_add_f32 v[184:185], v[184:185], v[240:241]
	v_pk_add_f32 v[186:187], v[186:187], v[242:243]
	v_pk_add_f32 v[188:189], v[188:189], v[244:245]
	s_mov_b64 s[0:1], 0x1401000
	v_lshl_add_u64 v[232:233], v[36:37], 0, s[0:1]
	global_load_dwordx4 v[224:227], v[232:233], off
	global_load_dwordx4 v[228:231], v[232:233], off offset:16
	global_load_dwordx4 v[238:241], v[232:233], off offset:2048
	global_load_dwordx4 v[242:245], v[232:233], off offset:2064
	s_waitcnt vmcnt(8)
	v_pk_add_f32 v[174:175], v[174:175], v[190:191]
	v_pk_add_f32 v[176:177], v[176:177], v[192:193]
	v_pk_add_f32 v[178:179], v[178:179], v[194:195]
	v_pk_add_f32 v[180:181], v[180:181], v[196:197]
	v_pk_add_f32 v[182:183], v[182:183], v[198:199]
	v_pk_add_f32 v[184:185], v[184:185], v[200:201]
	v_pk_add_f32 v[186:187], v[186:187], v[204:205]
	v_pk_add_f32 v[188:189], v[188:189], v[206:207]
	s_mov_b64 s[0:1], 0x1801000
	v_lshl_add_u64 v[232:233], v[36:37], 0, s[0:1]
	global_load_dwordx4 v[190:193], v[232:233], off
	global_load_dwordx4 v[194:197], v[232:233], off offset:16
	global_load_dwordx4 v[198:201], v[232:233], off offset:2048
	global_load_dwordx4 v[204:207], v[232:233], off offset:2064
	s_waitcnt vmcnt(8)
	v_pk_add_f32 v[174:175], v[174:175], v[208:209]
	v_pk_add_f32 v[176:177], v[176:177], v[210:211]
	v_pk_add_f32 v[178:179], v[178:179], v[212:213]
	v_pk_add_f32 v[180:181], v[180:181], v[214:215]
	v_pk_add_f32 v[182:183], v[182:183], v[216:217]
	v_pk_add_f32 v[184:185], v[184:185], v[218:219]
	v_pk_add_f32 v[186:187], v[186:187], v[220:221]
	v_pk_add_f32 v[188:189], v[188:189], v[222:223]
	s_mov_b64 s[0:1], 0x1c01000
	v_lshl_add_u64 v[232:233], v[36:37], 0, s[0:1]
	global_load_dwordx4 v[208:211], v[232:233], off
	global_load_dwordx4 v[212:215], v[232:233], off offset:16
	global_load_dwordx4 v[216:219], v[232:233], off offset:2048
	global_load_dwordx4 v[220:223], v[232:233], off offset:2064
	s_waitcnt vmcnt(8)
	v_pk_add_f32 v[174:175], v[174:175], v[224:225]
	v_pk_add_f32 v[176:177], v[176:177], v[226:227]
	v_pk_add_f32 v[178:179], v[178:179], v[228:229]
	v_pk_add_f32 v[180:181], v[180:181], v[230:231]
	v_pk_add_f32 v[182:183], v[182:183], v[238:239]
	v_pk_add_f32 v[184:185], v[184:185], v[240:241]
	v_pk_add_f32 v[186:187], v[186:187], v[242:243]
	v_pk_add_f32 v[188:189], v[188:189], v[244:245]
	global_load_dwordx4 v[224:227], v[76:77], off
	global_load_dwordx4 v[228:231], v[76:77], off offset:16
	global_load_dwordx4 v[238:241], v[78:79], off
	global_load_dwordx4 v[242:245], v[78:79], off offset:16
	s_waitcnt vmcnt(8)
	v_pk_add_f32 v[174:175], v[174:175], v[190:191]
	v_pk_add_f32 v[176:177], v[176:177], v[192:193]
	v_pk_add_f32 v[178:179], v[178:179], v[194:195]
	v_pk_add_f32 v[180:181], v[180:181], v[196:197]
	v_pk_add_f32 v[182:183], v[182:183], v[198:199]
	v_pk_add_f32 v[184:185], v[184:185], v[200:201]
	v_pk_add_f32 v[186:187], v[186:187], v[204:205]
	v_pk_add_f32 v[188:189], v[188:189], v[206:207]
	s_waitcnt vmcnt(4)
	v_pk_add_f32 v[174:175], v[174:175], v[208:209]
	v_pk_add_f32 v[176:177], v[176:177], v[210:211]
	v_pk_add_f32 v[178:179], v[178:179], v[212:213]
	v_pk_add_f32 v[180:181], v[180:181], v[214:215]
	v_pk_add_f32 v[182:183], v[182:183], v[216:217]
	v_pk_add_f32 v[184:185], v[184:185], v[218:219]
	v_pk_add_f32 v[186:187], v[186:187], v[220:221]
	v_pk_add_f32 v[188:189], v[188:189], v[222:223]
	s_waitcnt vmcnt(0)
	v_pk_fma_f32 v[44:45], v[174:175], v[224:225], v[44:45]
	v_pk_fma_f32 v[46:47], v[176:177], v[226:227], v[46:47]
	v_pk_fma_f32 v[42:43], v[178:179], v[228:229], v[42:43]
	v_pk_fma_f32 v[48:49], v[180:181], v[230:231], v[48:49]
	v_pk_fma_f32 v[38:39], v[182:183], v[238:239], v[38:39]
	v_pk_fma_f32 v[40:41], v[184:185], v[240:241], v[40:41]
	v_pk_fma_f32 v[32:33], v[186:187], v[242:243], v[32:33]
	v_pk_fma_f32 v[34:35], v[188:189], v[244:245], v[34:35]

.LBB0_777:
	s_add_i32 s0, s75, s4
	s_cmpk_lt_i32 s0, 0x4200
	s_cselect_b32 s0, s0, s4
	s_ashr_i32 s1, s0, 31
	s_lshl_b64 s[0:1], s[0:1], 12
	v_lshl_add_u64 v[32:33], v[80:81], 0, s[0:1]
	global_load_dwordx4 v[46:49], v[32:33], off
	global_load_dwordx4 v[42:45], v[32:33], off offset:1024
	global_load_dwordx4 v[38:41], v[32:33], off offset:2048
	global_load_dwordx4 v[34:37], v[32:33], off offset:3072
	s_waitcnt vmcnt(4)
	s_andn2_b64 vcc, exec, s[8:9]
	s_cbranch_vccnz .LBB0_767
	v_cvt_f32_f16_sdwa v167, v62 dst_sel:DWORD dst_unused:UNUSED_PAD src0_sel:WORD_1
	v_cvt_f32_f16_e32 v166, v62
	v_cvt_f32_f16_sdwa v163, v63 dst_sel:DWORD dst_unused:UNUSED_PAD src0_sel:WORD_1
	v_cvt_f32_f16_e32 v162, v63
	v_cvt_f32_f16_sdwa v161, v64 dst_sel:DWORD dst_unused:UNUSED_PAD src0_sel:WORD_1
	v_cvt_f32_f16_e32 v160, v64
	v_cvt_f32_f16_sdwa v165, v65 dst_sel:DWORD dst_unused:UNUSED_PAD src0_sel:WORD_1
	v_cvt_f32_f16_e32 v164, v65
	v_cvt_f32_f16_sdwa v155, v58 dst_sel:DWORD dst_unused:UNUSED_PAD src0_sel:WORD_1
	v_cvt_f32_f16_e32 v154, v58
	v_cvt_f32_f16_sdwa v157, v59 dst_sel:DWORD dst_unused:UNUSED_PAD src0_sel:WORD_1
	v_cvt_f32_f16_e32 v156, v59
	v_cvt_f32_f16_sdwa v153, v60 dst_sel:DWORD dst_unused:UNUSED_PAD src0_sel:WORD_1
	v_cvt_f32_f16_e32 v152, v60
	v_cvt_f32_f16_sdwa v159, v61 dst_sel:DWORD dst_unused:UNUSED_PAD src0_sel:WORD_1
	v_cvt_f32_f16_e32 v158, v61
	v_cvt_f32_f16_sdwa v61, v54 dst_sel:DWORD dst_unused:UNUSED_PAD src0_sel:WORD_1
	v_cvt_f32_f16_e32 v60, v54
	v_cvt_f32_f16_sdwa v63, v55 dst_sel:DWORD dst_unused:UNUSED_PAD src0_sel:WORD_1
	v_cvt_f32_f16_e32 v62, v55
	v_cvt_f32_f16_sdwa v59, v56 dst_sel:DWORD dst_unused:UNUSED_PAD src0_sel:WORD_1
	v_cvt_f32_f16_e32 v58, v56
	v_cvt_f32_f16_sdwa v65, v57 dst_sel:DWORD dst_unused:UNUSED_PAD src0_sel:WORD_1
	v_cvt_f32_f16_e32 v64, v57
	v_cvt_f32_f16_sdwa v55, v50 dst_sel:DWORD dst_unused:UNUSED_PAD src0_sel:WORD_1
	v_cvt_f32_f16_e32 v54, v50
	v_cvt_f32_f16_sdwa v57, v51 dst_sel:DWORD dst_unused:UNUSED_PAD src0_sel:WORD_1
	v_cvt_f32_f16_e32 v56, v51
	v_cvt_f32_f16_sdwa v33, v52 dst_sel:DWORD dst_unused:UNUSED_PAD src0_sel:WORD_1
	v_cvt_f32_f16_e32 v32, v52
	v_cvt_f32_f16_sdwa v51, v53 dst_sel:DWORD dst_unused:UNUSED_PAD src0_sel:WORD_1
	v_cvt_f32_f16_e32 v50, v53
	s_cmpk_gt_i32 s14, 0x3fff
	s_cselect_b64 s[2:3], -1, 0
	s_cmpk_lt_i32 s14, 0x4000
	s_cbranch_scc1 .LBB0_780
	s_add_i32 s86, s14, 0xffffc000
	s_lshl_b64 s[0:1], s[86:87], 13
	v_lshl_add_u64 v[52:53], v[82:83], 0, s[0:1]
	global_load_dwordx4 v[190:193], v[52:53], off
	global_load_dwordx4 v[194:197], v[52:53], off offset:16
	global_load_dwordx4 v[198:201], v[52:53], off offset:2048
	global_load_dwordx4 v[204:207], v[52:53], off offset:2064
	s_mov_b64 s[0:1], 0x400000
	v_lshl_add_u64 v[232:233], v[52:53], 0, s[0:1]
	global_load_dwordx4 v[208:211], v[232:233], off
	global_load_dwordx4 v[212:215], v[232:233], off offset:16
	global_load_dwordx4 v[216:219], v[232:233], off offset:2048
	global_load_dwordx4 v[220:223], v[232:233], off offset:2064
	s_mov_b64 s[0:1], 0x800000
	v_lshl_add_u64 v[232:233], v[52:53], 0, s[0:1]
	global_load_dwordx4 v[224:227], v[232:233], off
	global_load_dwordx4 v[228:231], v[232:233], off offset:16
	global_load_dwordx4 v[238:241], v[232:233], off offset:2048
	global_load_dwordx4 v[242:245], v[232:233], off offset:2064
	s_waitcnt vmcnt(8)
	v_mov_b64_e32 v[174:175], v[190:191]
	v_mov_b64_e32 v[176:177], v[192:193]
	v_mov_b64_e32 v[178:179], v[194:195]
	v_mov_b64_e32 v[180:181], v[196:197]
	v_mov_b64_e32 v[182:183], v[198:199]
	v_mov_b64_e32 v[184:185], v[200:201]
	v_mov_b64_e32 v[186:187], v[204:205]
	v_mov_b64_e32 v[188:189], v[206:207]
	s_mov_b64 s[0:1], 0xc00000
	v_lshl_add_u64 v[232:233], v[52:53], 0, s[0:1]
	global_load_dwordx4 v[190:193], v[232:233], off
	global_load_dwordx4 v[194:197], v[232:233], off offset:16
	global_load_dwordx4 v[198:201], v[232:233], off offset:2048
	global_load_dwordx4 v[204:207], v[232:233], off offset:2064
	s_waitcnt vmcnt(8)
	v_pk_add_f32 v[174:175], v[174:175], v[208:209]
	v_pk_add_f32 v[176:177], v[176:177], v[210:211]
	v_pk_add_f32 v[178:179], v[178:179], v[212:213]
	v_pk_add_f32 v[180:181], v[180:181], v[214:215]
	v_pk_add_f32 v[182:183], v[182:183], v[216:217]
	v_pk_add_f32 v[184:185], v[184:185], v[218:219]
	v_pk_add_f32 v[186:187], v[186:187], v[220:221]
	v_pk_add_f32 v[188:189], v[188:189], v[222:223]
	s_mov_b64 s[0:1], 0x1000000
	v_lshl_add_u64 v[232:233], v[52:53], 0, s[0:1]
	global_load_dwordx4 v[208:211], v[232:233], off
	global_load_dwordx4 v[212:215], v[232:233], off offset:16
	global_load_dwordx4 v[216:219], v[232:233], off offset:2048
	global_load_dwordx4 v[220:223], v[232:233], off offset:2064
	s_waitcnt vmcnt(8)
	v_pk_add_f32 v[174:175], v[174:175], v[224:225]
	v_pk_add_f32 v[176:177], v[176:177], v[226:227]
	v_pk_add_f32 v[178:179], v[178:179], v[228:229]
	v_pk_add_f32 v[180:181], v[180:181], v[230:231]
	v_pk_add_f32 v[182:183], v[182:183], v[238:239]
	v_pk_add_f32 v[184:185], v[184:185], v[240:241]
	v_pk_add_f32 v[186:187], v[186:187], v[242:243]
	v_pk_add_f32 v[188:189], v[188:189], v[244:245]
	s_mov_b64 s[0:1], 0x1400000
	v_lshl_add_u64 v[232:233], v[52:53], 0, s[0:1]
	global_load_dwordx4 v[224:227], v[232:233], off
	global_load_dwordx4 v[228:231], v[232:233], off offset:16
	global_load_dwordx4 v[238:241], v[232:233], off offset:2048
	global_load_dwordx4 v[242:245], v[232:233], off offset:2064
	s_waitcnt vmcnt(8)
	v_pk_add_f32 v[174:175], v[174:175], v[190:191]
	v_pk_add_f32 v[176:177], v[176:177], v[192:193]
	v_pk_add_f32 v[178:179], v[178:179], v[194:195]
	v_pk_add_f32 v[180:181], v[180:181], v[196:197]
	v_pk_add_f32 v[182:183], v[182:183], v[198:199]
	v_pk_add_f32 v[184:185], v[184:185], v[200:201]
	v_pk_add_f32 v[186:187], v[186:187], v[204:205]
	v_pk_add_f32 v[188:189], v[188:189], v[206:207]
	s_mov_b64 s[0:1], 0x1800000
	v_lshl_add_u64 v[232:233], v[52:53], 0, s[0:1]
	global_load_dwordx4 v[190:193], v[232:233], off
	global_load_dwordx4 v[194:197], v[232:233], off offset:16
	global_load_dwordx4 v[198:201], v[232:233], off offset:2048
	global_load_dwordx4 v[204:207], v[232:233], off offset:2064
	s_waitcnt vmcnt(8)
	v_pk_add_f32 v[174:175], v[174:175], v[208:209]
	v_pk_add_f32 v[176:177], v[176:177], v[210:211]
	v_pk_add_f32 v[178:179], v[178:179], v[212:213]
	v_pk_add_f32 v[180:181], v[180:181], v[214:215]
	v_pk_add_f32 v[182:183], v[182:183], v[216:217]
	v_pk_add_f32 v[184:185], v[184:185], v[218:219]
	v_pk_add_f32 v[186:187], v[186:187], v[220:221]
	v_pk_add_f32 v[188:189], v[188:189], v[222:223]
	s_mov_b64 s[0:1], 0x1c00000
	v_lshl_add_u64 v[232:233], v[52:53], 0, s[0:1]
	global_load_dwordx4 v[208:211], v[232:233], off
	global_load_dwordx4 v[212:215], v[232:233], off offset:16
	global_load_dwordx4 v[216:219], v[232:233], off offset:2048
	global_load_dwordx4 v[220:223], v[232:233], off offset:2064
	s_waitcnt vmcnt(8)
	v_pk_add_f32 v[174:175], v[174:175], v[224:225]
	v_pk_add_f32 v[176:177], v[176:177], v[226:227]
	v_pk_add_f32 v[178:179], v[178:179], v[228:229]
	v_pk_add_f32 v[180:181], v[180:181], v[230:231]
	v_pk_add_f32 v[182:183], v[182:183], v[238:239]
	v_pk_add_f32 v[184:185], v[184:185], v[240:241]
	v_pk_add_f32 v[186:187], v[186:187], v[242:243]
	v_pk_add_f32 v[188:189], v[188:189], v[244:245]
	global_load_dwordx4 v[224:227], v[74:75], off
	global_load_dwordx4 v[228:231], v[74:75], off offset:16
	global_load_dwordx4 v[238:241], v[74:75], off offset:2048
	global_load_dwordx4 v[242:245], v[74:75], off offset:2064
	s_waitcnt vmcnt(8)
	v_pk_add_f32 v[174:175], v[174:175], v[190:191]
	v_pk_add_f32 v[176:177], v[176:177], v[192:193]
	v_pk_add_f32 v[178:179], v[178:179], v[194:195]
	v_pk_add_f32 v[180:181], v[180:181], v[196:197]
	v_pk_add_f32 v[182:183], v[182:183], v[198:199]
	v_pk_add_f32 v[184:185], v[184:185], v[200:201]
	v_pk_add_f32 v[186:187], v[186:187], v[204:205]
	v_pk_add_f32 v[188:189], v[188:189], v[206:207]
	s_mov_b64 s[0:1], 0x1000
	v_lshl_add_u64 v[232:233], v[52:53], 0, s[0:1]
	global_load_dwordx4 v[190:193], v[232:233], off
	global_load_dwordx4 v[194:197], v[232:233], off offset:16
	global_load_dwordx4 v[198:201], v[232:233], off offset:2048
	global_load_dwordx4 v[204:207], v[232:233], off offset:2064
	s_waitcnt vmcnt(8)
	v_pk_add_f32 v[174:175], v[174:175], v[208:209]
	v_pk_add_f32 v[176:177], v[176:177], v[210:211]
	v_pk_add_f32 v[178:179], v[178:179], v[212:213]
	v_pk_add_f32 v[180:181], v[180:181], v[214:215]
	v_pk_add_f32 v[182:183], v[182:183], v[216:217]
	v_pk_add_f32 v[184:185], v[184:185], v[218:219]
	v_pk_add_f32 v[186:187], v[186:187], v[220:221]
	v_pk_add_f32 v[188:189], v[188:189], v[222:223]
	s_mov_b64 s[0:1], 0x401000
	v_lshl_add_u64 v[232:233], v[52:53], 0, s[0:1]
	global_load_dwordx4 v[208:211], v[232:233], off
	global_load_dwordx4 v[212:215], v[232:233], off offset:16
	global_load_dwordx4 v[216:219], v[232:233], off offset:2048
	global_load_dwordx4 v[220:223], v[232:233], off offset:2064
	s_waitcnt vmcnt(8)
	v_pk_fma_f32 v[166:167], v[174:175], v[224:225], v[166:167]
	v_pk_fma_f32 v[162:163], v[176:177], v[226:227], v[162:163]
	v_pk_fma_f32 v[160:161], v[178:179], v[228:229], v[160:161]
	v_pk_fma_f32 v[164:165], v[180:181], v[230:231], v[164:165]
	v_pk_fma_f32 v[154:155], v[182:183], v[238:239], v[154:155]
	v_pk_fma_f32 v[156:157], v[184:185], v[240:241], v[156:157]
	v_pk_fma_f32 v[152:153], v[186:187], v[242:243], v[152:153]
	v_pk_fma_f32 v[158:159], v[188:189], v[244:245], v[158:159]
	s_mov_b64 s[0:1], 0x801000
	v_lshl_add_u64 v[232:233], v[52:53], 0, s[0:1]
	global_load_dwordx4 v[224:227], v[232:233], off
	global_load_dwordx4 v[228:231], v[232:233], off offset:16
	global_load_dwordx4 v[238:241], v[232:233], off offset:2048
	global_load_dwordx4 v[242:245], v[232:233], off offset:2064
	s_waitcnt vmcnt(8)
	v_mov_b64_e32 v[174:175], v[190:191]
	v_mov_b64_e32 v[176:177], v[192:193]
	v_mov_b64_e32 v[178:179], v[194:195]
	v_mov_b64_e32 v[180:181], v[196:197]
	v_mov_b64_e32 v[182:183], v[198:199]
	v_mov_b64_e32 v[184:185], v[200:201]
	v_mov_b64_e32 v[186:187], v[204:205]
	v_mov_b64_e32 v[188:189], v[206:207]
	s_mov_b64 s[0:1], 0xc01000
	v_lshl_add_u64 v[232:233], v[52:53], 0, s[0:1]
	global_load_dwordx4 v[190:193], v[232:233], off
	global_load_dwordx4 v[194:197], v[232:233], off offset:16
	global_load_dwordx4 v[198:201], v[232:233], off offset:2048
	global_load_dwordx4 v[204:207], v[232:233], off offset:2064
	s_waitcnt vmcnt(8)
	v_pk_add_f32 v[174:175], v[174:175], v[208:209]
	v_pk_add_f32 v[176:177], v[176:177], v[210:211]
	v_pk_add_f32 v[178:179], v[178:179], v[212:213]
	v_pk_add_f32 v[180:181], v[180:181], v[214:215]
	v_pk_add_f32 v[182:183], v[182:183], v[216:217]
	v_pk_add_f32 v[184:185], v[184:185], v[218:219]
	v_pk_add_f32 v[186:187], v[186:187], v[220:221]
	v_pk_add_f32 v[188:189], v[188:189], v[222:223]
	s_mov_b64 s[0:1], 0x1001000
	v_lshl_add_u64 v[232:233], v[52:53], 0, s[0:1]
	global_load_dwordx4 v[208:211], v[232:233], off
	global_load_dwordx4 v[212:215], v[232:233], off offset:16
	global_load_dwordx4 v[216:219], v[232:233], off offset:2048
	global_load_dwordx4 v[220:223], v[232:233], off offset:2064
	s_waitcnt vmcnt(8)
	v_pk_add_f32 v[174:175], v[174:175], v[224:225]
	v_pk_add_f32 v[176:177], v[176:177], v[226:227]
	v_pk_add_f32 v[178:179], v[178:179], v[228:229]
	v_pk_add_f32 v[180:181], v[180:181], v[230:231]
	v_pk_add_f32 v[182:183], v[182:183], v[238:239]
	v_pk_add_f32 v[184:185], v[184:185], v[240:241]
	v_pk_add_f32 v[186:187], v[186:187], v[242:243]
	v_pk_add_f32 v[188:189], v[188:189], v[244:245]
	s_mov_b64 s[0:1], 0x1401000
	v_lshl_add_u64 v[232:233], v[52:53], 0, s[0:1]
	global_load_dwordx4 v[224:227], v[232:233], off
	global_load_dwordx4 v[228:231], v[232:233], off offset:16
	global_load_dwordx4 v[238:241], v[232:233], off offset:2048
	global_load_dwordx4 v[242:245], v[232:233], off offset:2064
	s_waitcnt vmcnt(8)
	v_pk_add_f32 v[174:175], v[174:175], v[190:191]
	v_pk_add_f32 v[176:177], v[176:177], v[192:193]
	v_pk_add_f32 v[178:179], v[178:179], v[194:195]
	v_pk_add_f32 v[180:181], v[180:181], v[196:197]
	v_pk_add_f32 v[182:183], v[182:183], v[198:199]
	v_pk_add_f32 v[184:185], v[184:185], v[200:201]
	v_pk_add_f32 v[186:187], v[186:187], v[204:205]
	v_pk_add_f32 v[188:189], v[188:189], v[206:207]
	s_mov_b64 s[0:1], 0x1801000
	v_lshl_add_u64 v[232:233], v[52:53], 0, s[0:1]
	global_load_dwordx4 v[190:193], v[232:233], off
	global_load_dwordx4 v[194:197], v[232:233], off offset:16
	global_load_dwordx4 v[198:201], v[232:233], off offset:2048
	global_load_dwordx4 v[204:207], v[232:233], off offset:2064
	s_waitcnt vmcnt(8)
	v_pk_add_f32 v[174:175], v[174:175], v[208:209]
	v_pk_add_f32 v[176:177], v[176:177], v[210:211]
	v_pk_add_f32 v[178:179], v[178:179], v[212:213]
	v_pk_add_f32 v[180:181], v[180:181], v[214:215]
	v_pk_add_f32 v[182:183], v[182:183], v[216:217]
	v_pk_add_f32 v[184:185], v[184:185], v[218:219]
	v_pk_add_f32 v[186:187], v[186:187], v[220:221]
	v_pk_add_f32 v[188:189], v[188:189], v[222:223]
	s_mov_b64 s[0:1], 0x1c01000
	v_lshl_add_u64 v[232:233], v[52:53], 0, s[0:1]
	global_load_dwordx4 v[208:211], v[232:233], off
	global_load_dwordx4 v[212:215], v[232:233], off offset:16
	global_load_dwordx4 v[216:219], v[232:233], off offset:2048
	global_load_dwordx4 v[220:223], v[232:233], off offset:2064
	s_waitcnt vmcnt(8)
	v_pk_add_f32 v[174:175], v[174:175], v[224:225]
	v_pk_add_f32 v[176:177], v[176:177], v[226:227]
	v_pk_add_f32 v[178:179], v[178:179], v[228:229]
	v_pk_add_f32 v[180:181], v[180:181], v[230:231]
	v_pk_add_f32 v[182:183], v[182:183], v[238:239]
	v_pk_add_f32 v[184:185], v[184:185], v[240:241]
	v_pk_add_f32 v[186:187], v[186:187], v[242:243]
	v_pk_add_f32 v[188:189], v[188:189], v[244:245]
	global_load_dwordx4 v[224:227], v[76:77], off
	global_load_dwordx4 v[228:231], v[76:77], off offset:16
	global_load_dwordx4 v[238:241], v[78:79], off
	global_load_dwordx4 v[242:245], v[78:79], off offset:16
	s_waitcnt vmcnt(8)
	v_pk_add_f32 v[174:175], v[174:175], v[190:191]
	v_pk_add_f32 v[176:177], v[176:177], v[192:193]
	v_pk_add_f32 v[178:179], v[178:179], v[194:195]
	v_pk_add_f32 v[180:181], v[180:181], v[196:197]
	v_pk_add_f32 v[182:183], v[182:183], v[198:199]
	v_pk_add_f32 v[184:185], v[184:185], v[200:201]
	v_pk_add_f32 v[186:187], v[186:187], v[204:205]
	v_pk_add_f32 v[188:189], v[188:189], v[206:207]
	s_waitcnt vmcnt(4)
	v_pk_add_f32 v[174:175], v[174:175], v[208:209]
	v_pk_add_f32 v[176:177], v[176:177], v[210:211]
	v_pk_add_f32 v[178:179], v[178:179], v[212:213]
	v_pk_add_f32 v[180:181], v[180:181], v[214:215]
	v_pk_add_f32 v[182:183], v[182:183], v[216:217]
	v_pk_add_f32 v[184:185], v[184:185], v[218:219]
	v_pk_add_f32 v[186:187], v[186:187], v[220:221]
	v_pk_add_f32 v[188:189], v[188:189], v[222:223]
	s_waitcnt vmcnt(0)
	v_pk_fma_f32 v[60:61], v[174:175], v[224:225], v[60:61]
	v_pk_fma_f32 v[62:63], v[176:177], v[226:227], v[62:63]
	v_pk_fma_f32 v[58:59], v[178:179], v[228:229], v[58:59]
	v_pk_fma_f32 v[64:65], v[180:181], v[230:231], v[64:65]
	v_pk_fma_f32 v[54:55], v[182:183], v[238:239], v[54:55]
	v_pk_fma_f32 v[56:57], v[184:185], v[240:241], v[56:57]
	v_pk_fma_f32 v[32:33], v[186:187], v[242:243], v[32:33]
	v_pk_fma_f32 v[50:51], v[188:189], v[244:245], v[50:51]

.LBB0_1049:
	s_add_i32 s16, s8, s94
	s_cmpk_lt_i32 s16, 0x4200
	s_cselect_b64 s[14:15], -1, 0
	s_and_b64 s[0:1], s[14:15], exec
	s_cselect_b32 s10, s16, s8
	s_ashr_i32 s11, s10, 31
	s_lshl_b64 s[0:1], s[10:11], 12
	v_lshl_add_u64 v[32:33], v[80:81], 0, s[0:1]
	s_waitcnt vmcnt(0)
	global_load_dwordx4 v[62:65], v[32:33], off
	global_load_dwordx4 v[58:61], v[32:33], off offset:1024
	global_load_dwordx4 v[54:57], v[32:33], off offset:2048
	global_load_dwordx4 v[50:53], v[32:33], off offset:3072
	v_cvt_f32_f16_sdwa v167, v46 dst_sel:DWORD dst_unused:UNUSED_PAD src0_sel:WORD_1
	v_cvt_f32_f16_e32 v166, v46
	v_cvt_f32_f16_sdwa v163, v47 dst_sel:DWORD dst_unused:UNUSED_PAD src0_sel:WORD_1
	v_cvt_f32_f16_e32 v162, v47
	v_cvt_f32_f16_sdwa v161, v48 dst_sel:DWORD dst_unused:UNUSED_PAD src0_sel:WORD_1
	v_cvt_f32_f16_e32 v160, v48
	v_cvt_f32_f16_sdwa v165, v49 dst_sel:DWORD dst_unused:UNUSED_PAD src0_sel:WORD_1
	v_cvt_f32_f16_e32 v164, v49
	v_cvt_f32_f16_sdwa v155, v42 dst_sel:DWORD dst_unused:UNUSED_PAD src0_sel:WORD_1
	v_cvt_f32_f16_e32 v154, v42
	v_cvt_f32_f16_sdwa v157, v43 dst_sel:DWORD dst_unused:UNUSED_PAD src0_sel:WORD_1
	v_cvt_f32_f16_e32 v156, v43
	v_cvt_f32_f16_sdwa v153, v44 dst_sel:DWORD dst_unused:UNUSED_PAD src0_sel:WORD_1
	v_cvt_f32_f16_e32 v152, v44
	v_cvt_f32_f16_sdwa v159, v45 dst_sel:DWORD dst_unused:UNUSED_PAD src0_sel:WORD_1
	v_cvt_f32_f16_e32 v158, v45
	v_cvt_f32_f16_sdwa v45, v38 dst_sel:DWORD dst_unused:UNUSED_PAD src0_sel:WORD_1
	v_cvt_f32_f16_e32 v44, v38
	v_cvt_f32_f16_sdwa v47, v39 dst_sel:DWORD dst_unused:UNUSED_PAD src0_sel:WORD_1
	v_cvt_f32_f16_e32 v46, v39
	v_cvt_f32_f16_sdwa v43, v40 dst_sel:DWORD dst_unused:UNUSED_PAD src0_sel:WORD_1
	v_cvt_f32_f16_e32 v42, v40
	v_cvt_f32_f16_sdwa v49, v41 dst_sel:DWORD dst_unused:UNUSED_PAD src0_sel:WORD_1
	v_cvt_f32_f16_e32 v48, v41
	v_cvt_f32_f16_sdwa v39, v34 dst_sel:DWORD dst_unused:UNUSED_PAD src0_sel:WORD_1
	v_cvt_f32_f16_e32 v38, v34
	v_cvt_f32_f16_sdwa v41, v35 dst_sel:DWORD dst_unused:UNUSED_PAD src0_sel:WORD_1
	v_cvt_f32_f16_e32 v40, v35
	v_cvt_f32_f16_sdwa v33, v36 dst_sel:DWORD dst_unused:UNUSED_PAD src0_sel:WORD_1
	v_cvt_f32_f16_e32 v32, v36
	v_cvt_f32_f16_sdwa v35, v37 dst_sel:DWORD dst_unused:UNUSED_PAD src0_sel:WORD_1
	v_cvt_f32_f16_e32 v34, v37
	s_cmpk_gt_i32 s8, 0x3fff
	s_cselect_b64 s[2:3], -1, 0
	s_cmpk_lt_i32 s8, 0x4000
	s_cbranch_scc1 .LBB0_1051
	s_add_i32 s86, s8, 0xffffc000
	s_lshl_b64 s[0:1], s[86:87], 13
	v_lshl_add_u64 v[36:37], v[82:83], 0, s[0:1]
	global_load_dwordx4 v[190:193], v[36:37], off
	global_load_dwordx4 v[194:197], v[36:37], off offset:16
	global_load_dwordx4 v[198:201], v[36:37], off offset:2048
	global_load_dwordx4 v[204:207], v[36:37], off offset:2064
	s_mov_b64 s[0:1], 0x400000
	v_lshl_add_u64 v[232:233], v[36:37], 0, s[0:1]
	global_load_dwordx4 v[208:211], v[232:233], off
	global_load_dwordx4 v[212:215], v[232:233], off offset:16
	global_load_dwordx4 v[216:219], v[232:233], off offset:2048
	global_load_dwordx4 v[220:223], v[232:233], off offset:2064
	s_mov_b64 s[0:1], 0x800000
	v_lshl_add_u64 v[232:233], v[36:37], 0, s[0:1]
	global_load_dwordx4 v[224:227], v[232:233], off
	global_load_dwordx4 v[228:231], v[232:233], off offset:16
	global_load_dwordx4 v[238:241], v[232:233], off offset:2048
	global_load_dwordx4 v[242:245], v[232:233], off offset:2064
	s_waitcnt vmcnt(8)
	v_mov_b64_e32 v[174:175], v[190:191]
	v_mov_b64_e32 v[176:177], v[192:193]
	v_mov_b64_e32 v[178:179], v[194:195]
	v_mov_b64_e32 v[180:181], v[196:197]
	v_mov_b64_e32 v[182:183], v[198:199]
	v_mov_b64_e32 v[184:185], v[200:201]
	v_mov_b64_e32 v[186:187], v[204:205]
	v_mov_b64_e32 v[188:189], v[206:207]
	s_mov_b64 s[0:1], 0xc00000
	v_lshl_add_u64 v[232:233], v[36:37], 0, s[0:1]
	global_load_dwordx4 v[190:193], v[232:233], off
	global_load_dwordx4 v[194:197], v[232:233], off offset:16
	global_load_dwordx4 v[198:201], v[232:233], off offset:2048
	global_load_dwordx4 v[204:207], v[232:233], off offset:2064
	s_waitcnt vmcnt(8)
	v_pk_add_f32 v[174:175], v[174:175], v[208:209]
	v_pk_add_f32 v[176:177], v[176:177], v[210:211]
	v_pk_add_f32 v[178:179], v[178:179], v[212:213]
	v_pk_add_f32 v[180:181], v[180:181], v[214:215]
	v_pk_add_f32 v[182:183], v[182:183], v[216:217]
	v_pk_add_f32 v[184:185], v[184:185], v[218:219]
	v_pk_add_f32 v[186:187], v[186:187], v[220:221]
	v_pk_add_f32 v[188:189], v[188:189], v[222:223]
	s_mov_b64 s[0:1], 0x1000000
	v_lshl_add_u64 v[232:233], v[36:37], 0, s[0:1]
	global_load_dwordx4 v[208:211], v[232:233], off
	global_load_dwordx4 v[212:215], v[232:233], off offset:16
	global_load_dwordx4 v[216:219], v[232:233], off offset:2048
	global_load_dwordx4 v[220:223], v[232:233], off offset:2064
	s_waitcnt vmcnt(8)
	v_pk_add_f32 v[174:175], v[174:175], v[224:225]
	v_pk_add_f32 v[176:177], v[176:177], v[226:227]
	v_pk_add_f32 v[178:179], v[178:179], v[228:229]
	v_pk_add_f32 v[180:181], v[180:181], v[230:231]
	v_pk_add_f32 v[182:183], v[182:183], v[238:239]
	v_pk_add_f32 v[184:185], v[184:185], v[240:241]
	v_pk_add_f32 v[186:187], v[186:187], v[242:243]
	v_pk_add_f32 v[188:189], v[188:189], v[244:245]
	s_mov_b64 s[0:1], 0x1400000
	v_lshl_add_u64 v[232:233], v[36:37], 0, s[0:1]
	global_load_dwordx4 v[224:227], v[232:233], off
	global_load_dwordx4 v[228:231], v[232:233], off offset:16
	global_load_dwordx4 v[238:241], v[232:233], off offset:2048
	global_load_dwordx4 v[242:245], v[232:233], off offset:2064
	s_waitcnt vmcnt(8)
	v_pk_add_f32 v[174:175], v[174:175], v[190:191]
	v_pk_add_f32 v[176:177], v[176:177], v[192:193]
	v_pk_add_f32 v[178:179], v[178:179], v[194:195]
	v_pk_add_f32 v[180:181], v[180:181], v[196:197]
	v_pk_add_f32 v[182:183], v[182:183], v[198:199]
	v_pk_add_f32 v[184:185], v[184:185], v[200:201]
	v_pk_add_f32 v[186:187], v[186:187], v[204:205]
	v_pk_add_f32 v[188:189], v[188:189], v[206:207]
	s_mov_b64 s[0:1], 0x1800000
	v_lshl_add_u64 v[232:233], v[36:37], 0, s[0:1]
	global_load_dwordx4 v[190:193], v[232:233], off
	global_load_dwordx4 v[194:197], v[232:233], off offset:16
	global_load_dwordx4 v[198:201], v[232:233], off offset:2048
	global_load_dwordx4 v[204:207], v[232:233], off offset:2064
	s_waitcnt vmcnt(8)
	v_pk_add_f32 v[174:175], v[174:175], v[208:209]
	v_pk_add_f32 v[176:177], v[176:177], v[210:211]
	v_pk_add_f32 v[178:179], v[178:179], v[212:213]
	v_pk_add_f32 v[180:181], v[180:181], v[214:215]
	v_pk_add_f32 v[182:183], v[182:183], v[216:217]
	v_pk_add_f32 v[184:185], v[184:185], v[218:219]
	v_pk_add_f32 v[186:187], v[186:187], v[220:221]
	v_pk_add_f32 v[188:189], v[188:189], v[222:223]
	s_mov_b64 s[0:1], 0x1c00000
	v_lshl_add_u64 v[232:233], v[36:37], 0, s[0:1]
	global_load_dwordx4 v[208:211], v[232:233], off
	global_load_dwordx4 v[212:215], v[232:233], off offset:16
	global_load_dwordx4 v[216:219], v[232:233], off offset:2048
	global_load_dwordx4 v[220:223], v[232:233], off offset:2064
	s_waitcnt vmcnt(8)
	v_pk_add_f32 v[174:175], v[174:175], v[224:225]
	v_pk_add_f32 v[176:177], v[176:177], v[226:227]
	v_pk_add_f32 v[178:179], v[178:179], v[228:229]
	v_pk_add_f32 v[180:181], v[180:181], v[230:231]
	v_pk_add_f32 v[182:183], v[182:183], v[238:239]
	v_pk_add_f32 v[184:185], v[184:185], v[240:241]
	v_pk_add_f32 v[186:187], v[186:187], v[242:243]
	v_pk_add_f32 v[188:189], v[188:189], v[244:245]
	s_mov_b64 s[0:1], 0x2000000
	v_lshl_add_u64 v[232:233], v[36:37], 0, s[0:1]
	global_load_dwordx4 v[224:227], v[232:233], off
	global_load_dwordx4 v[228:231], v[232:233], off offset:16
	global_load_dwordx4 v[238:241], v[232:233], off offset:2048
	global_load_dwordx4 v[242:245], v[232:233], off offset:2064
	s_waitcnt vmcnt(8)
	v_pk_add_f32 v[174:175], v[174:175], v[190:191]
	v_pk_add_f32 v[176:177], v[176:177], v[192:193]
	v_pk_add_f32 v[178:179], v[178:179], v[194:195]
	v_pk_add_f32 v[180:181], v[180:181], v[196:197]
	v_pk_add_f32 v[182:183], v[182:183], v[198:199]
	v_pk_add_f32 v[184:185], v[184:185], v[200:201]
	v_pk_add_f32 v[186:187], v[186:187], v[204:205]
	v_pk_add_f32 v[188:189], v[188:189], v[206:207]
	s_mov_b64 s[0:1], 0x2400000
	v_lshl_add_u64 v[232:233], v[36:37], 0, s[0:1]
	global_load_dwordx4 v[190:193], v[232:233], off
	global_load_dwordx4 v[194:197], v[232:233], off offset:16
	global_load_dwordx4 v[198:201], v[232:233], off offset:2048
	global_load_dwordx4 v[204:207], v[232:233], off offset:2064
	s_waitcnt vmcnt(8)
	v_pk_add_f32 v[174:175], v[174:175], v[208:209]
	v_pk_add_f32 v[176:177], v[176:177], v[210:211]
	v_pk_add_f32 v[178:179], v[178:179], v[212:213]
	v_pk_add_f32 v[180:181], v[180:181], v[214:215]
	v_pk_add_f32 v[182:183], v[182:183], v[216:217]
	v_pk_add_f32 v[184:185], v[184:185], v[218:219]
	v_pk_add_f32 v[186:187], v[186:187], v[220:221]
	v_pk_add_f32 v[188:189], v[188:189], v[222:223]
	s_mov_b64 s[0:1], 0x2800000
	v_lshl_add_u64 v[232:233], v[36:37], 0, s[0:1]
	global_load_dwordx4 v[208:211], v[232:233], off
	global_load_dwordx4 v[212:215], v[232:233], off offset:16
	global_load_dwordx4 v[216:219], v[232:233], off offset:2048
	global_load_dwordx4 v[220:223], v[232:233], off offset:2064
	s_waitcnt vmcnt(8)
	v_pk_add_f32 v[174:175], v[174:175], v[224:225]
	v_pk_add_f32 v[176:177], v[176:177], v[226:227]
	v_pk_add_f32 v[178:179], v[178:179], v[228:229]
	v_pk_add_f32 v[180:181], v[180:181], v[230:231]
	v_pk_add_f32 v[182:183], v[182:183], v[238:239]
	v_pk_add_f32 v[184:185], v[184:185], v[240:241]
	v_pk_add_f32 v[186:187], v[186:187], v[242:243]
	v_pk_add_f32 v[188:189], v[188:189], v[244:245]
	global_load_dwordx4 v[224:227], v[74:75], off
	global_load_dwordx4 v[228:231], v[74:75], off offset:16
	global_load_dwordx4 v[238:241], v[74:75], off offset:2048
	global_load_dwordx4 v[242:245], v[74:75], off offset:2064
	s_waitcnt vmcnt(8)
	v_pk_add_f32 v[174:175], v[174:175], v[190:191]
	v_pk_add_f32 v[176:177], v[176:177], v[192:193]
	v_pk_add_f32 v[178:179], v[178:179], v[194:195]
	v_pk_add_f32 v[180:181], v[180:181], v[196:197]
	v_pk_add_f32 v[182:183], v[182:183], v[198:199]
	v_pk_add_f32 v[184:185], v[184:185], v[200:201]
	v_pk_add_f32 v[186:187], v[186:187], v[204:205]
	v_pk_add_f32 v[188:189], v[188:189], v[206:207]
	s_mov_b64 s[0:1], 0x1000
	v_lshl_add_u64 v[232:233], v[36:37], 0, s[0:1]
	global_load_dwordx4 v[190:193], v[232:233], off
	global_load_dwordx4 v[194:197], v[232:233], off offset:16
	global_load_dwordx4 v[198:201], v[232:233], off offset:2048
	global_load_dwordx4 v[204:207], v[232:233], off offset:2064
	s_waitcnt vmcnt(8)
	v_pk_add_f32 v[174:175], v[174:175], v[208:209]
	v_pk_add_f32 v[176:177], v[176:177], v[210:211]
	v_pk_add_f32 v[178:179], v[178:179], v[212:213]
	v_pk_add_f32 v[180:181], v[180:181], v[214:215]
	v_pk_add_f32 v[182:183], v[182:183], v[216:217]
	v_pk_add_f32 v[184:185], v[184:185], v[218:219]
	v_pk_add_f32 v[186:187], v[186:187], v[220:221]
	v_pk_add_f32 v[188:189], v[188:189], v[222:223]
	s_mov_b64 s[0:1], 0x401000
	v_lshl_add_u64 v[232:233], v[36:37], 0, s[0:1]
	global_load_dwordx4 v[208:211], v[232:233], off
	global_load_dwordx4 v[212:215], v[232:233], off offset:16
	global_load_dwordx4 v[216:219], v[232:233], off offset:2048
	global_load_dwordx4 v[220:223], v[232:233], off offset:2064
	s_waitcnt vmcnt(8)
	v_pk_fma_f32 v[166:167], v[174:175], v[224:225], v[166:167]
	v_pk_fma_f32 v[162:163], v[176:177], v[226:227], v[162:163]
	v_pk_fma_f32 v[160:161], v[178:179], v[228:229], v[160:161]
	v_pk_fma_f32 v[164:165], v[180:181], v[230:231], v[164:165]
	v_pk_fma_f32 v[154:155], v[182:183], v[238:239], v[154:155]
	v_pk_fma_f32 v[156:157], v[184:185], v[240:241], v[156:157]
	v_pk_fma_f32 v[152:153], v[186:187], v[242:243], v[152:153]
	v_pk_fma_f32 v[158:159], v[188:189], v[244:245], v[158:159]
	s_mov_b64 s[0:1], 0x801000
	v_lshl_add_u64 v[232:233], v[36:37], 0, s[0:1]
	global_load_dwordx4 v[224:227], v[232:233], off
	global_load_dwordx4 v[228:231], v[232:233], off offset:16
	global_load_dwordx4 v[238:241], v[232:233], off offset:2048
	global_load_dwordx4 v[242:245], v[232:233], off offset:2064
	s_waitcnt vmcnt(8)
	v_mov_b64_e32 v[174:175], v[190:191]
	v_mov_b64_e32 v[176:177], v[192:193]
	v_mov_b64_e32 v[178:179], v[194:195]
	v_mov_b64_e32 v[180:181], v[196:197]
	v_mov_b64_e32 v[182:183], v[198:199]
	v_mov_b64_e32 v[184:185], v[200:201]
	v_mov_b64_e32 v[186:187], v[204:205]
	v_mov_b64_e32 v[188:189], v[206:207]
	s_mov_b64 s[0:1], 0xc01000
	v_lshl_add_u64 v[232:233], v[36:37], 0, s[0:1]
	global_load_dwordx4 v[190:193], v[232:233], off
	global_load_dwordx4 v[194:197], v[232:233], off offset:16
	global_load_dwordx4 v[198:201], v[232:233], off offset:2048
	global_load_dwordx4 v[204:207], v[232:233], off offset:2064
	s_waitcnt vmcnt(8)
	v_pk_add_f32 v[174:175], v[174:175], v[208:209]
	v_pk_add_f32 v[176:177], v[176:177], v[210:211]
	v_pk_add_f32 v[178:179], v[178:179], v[212:213]
	v_pk_add_f32 v[180:181], v[180:181], v[214:215]
	v_pk_add_f32 v[182:183], v[182:183], v[216:217]
	v_pk_add_f32 v[184:185], v[184:185], v[218:219]
	v_pk_add_f32 v[186:187], v[186:187], v[220:221]
	v_pk_add_f32 v[188:189], v[188:189], v[222:223]
	s_mov_b64 s[0:1], 0x1001000
	v_lshl_add_u64 v[232:233], v[36:37], 0, s[0:1]
	global_load_dwordx4 v[208:211], v[232:233], off
	global_load_dwordx4 v[212:215], v[232:233], off offset:16
	global_load_dwordx4 v[216:219], v[232:233], off offset:2048
	global_load_dwordx4 v[220:223], v[232:233], off offset:2064
	s_waitcnt vmcnt(8)
	v_pk_add_f32 v[174:175], v[174:175], v[224:225]
	v_pk_add_f32 v[176:177], v[176:177], v[226:227]
	v_pk_add_f32 v[178:179], v[178:179], v[228:229]
	v_pk_add_f32 v[180:181], v[180:181], v[230:231]
	v_pk_add_f32 v[182:183], v[182:183], v[238:239]
	v_pk_add_f32 v[184:185], v[184:185], v[240:241]
	v_pk_add_f32 v[186:187], v[186:187], v[242:243]
	v_pk_add_f32 v[188:189], v[188:189], v[244:245]
	s_mov_b64 s[0:1], 0x1401000
	v_lshl_add_u64 v[232:233], v[36:37], 0, s[0:1]
	global_load_dwordx4 v[224:227], v[232:233], off
	global_load_dwordx4 v[228:231], v[232:233], off offset:16
	global_load_dwordx4 v[238:241], v[232:233], off offset:2048
	global_load_dwordx4 v[242:245], v[232:233], off offset:2064
	s_waitcnt vmcnt(8)
	v_pk_add_f32 v[174:175], v[174:175], v[190:191]
	v_pk_add_f32 v[176:177], v[176:177], v[192:193]
	v_pk_add_f32 v[178:179], v[178:179], v[194:195]
	v_pk_add_f32 v[180:181], v[180:181], v[196:197]
	v_pk_add_f32 v[182:183], v[182:183], v[198:199]
	v_pk_add_f32 v[184:185], v[184:185], v[200:201]
	v_pk_add_f32 v[186:187], v[186:187], v[204:205]
	v_pk_add_f32 v[188:189], v[188:189], v[206:207]
	s_mov_b64 s[0:1], 0x1801000
	v_lshl_add_u64 v[232:233], v[36:37], 0, s[0:1]
	global_load_dwordx4 v[190:193], v[232:233], off
	global_load_dwordx4 v[194:197], v[232:233], off offset:16
	global_load_dwordx4 v[198:201], v[232:233], off offset:2048
	global_load_dwordx4 v[204:207], v[232:233], off offset:2064
	s_waitcnt vmcnt(8)
	v_pk_add_f32 v[174:175], v[174:175], v[208:209]
	v_pk_add_f32 v[176:177], v[176:177], v[210:211]
	v_pk_add_f32 v[178:179], v[178:179], v[212:213]
	v_pk_add_f32 v[180:181], v[180:181], v[214:215]
	v_pk_add_f32 v[182:183], v[182:183], v[216:217]
	v_pk_add_f32 v[184:185], v[184:185], v[218:219]
	v_pk_add_f32 v[186:187], v[186:187], v[220:221]
	v_pk_add_f32 v[188:189], v[188:189], v[222:223]
	s_mov_b64 s[0:1], 0x1c01000
	v_lshl_add_u64 v[232:233], v[36:37], 0, s[0:1]
	global_load_dwordx4 v[208:211], v[232:233], off
	global_load_dwordx4 v[212:215], v[232:233], off offset:16
	global_load_dwordx4 v[216:219], v[232:233], off offset:2048
	global_load_dwordx4 v[220:223], v[232:233], off offset:2064
	s_waitcnt vmcnt(8)
	v_pk_add_f32 v[174:175], v[174:175], v[224:225]
	v_pk_add_f32 v[176:177], v[176:177], v[226:227]
	v_pk_add_f32 v[178:179], v[178:179], v[228:229]
	v_pk_add_f32 v[180:181], v[180:181], v[230:231]
	v_pk_add_f32 v[182:183], v[182:183], v[238:239]
	v_pk_add_f32 v[184:185], v[184:185], v[240:241]
	v_pk_add_f32 v[186:187], v[186:187], v[242:243]
	v_pk_add_f32 v[188:189], v[188:189], v[244:245]
	s_mov_b64 s[0:1], 0x2001000
	v_lshl_add_u64 v[232:233], v[36:37], 0, s[0:1]
	global_load_dwordx4 v[224:227], v[232:233], off
	global_load_dwordx4 v[228:231], v[232:233], off offset:16
	global_load_dwordx4 v[238:241], v[232:233], off offset:2048
	global_load_dwordx4 v[242:245], v[232:233], off offset:2064
	s_waitcnt vmcnt(8)
	v_pk_add_f32 v[174:175], v[174:175], v[190:191]
	v_pk_add_f32 v[176:177], v[176:177], v[192:193]
	v_pk_add_f32 v[178:179], v[178:179], v[194:195]
	v_pk_add_f32 v[180:181], v[180:181], v[196:197]
	v_pk_add_f32 v[182:183], v[182:183], v[198:199]
	v_pk_add_f32 v[184:185], v[184:185], v[200:201]
	v_pk_add_f32 v[186:187], v[186:187], v[204:205]
	v_pk_add_f32 v[188:189], v[188:189], v[206:207]
	s_mov_b64 s[0:1], 0x2401000
	v_lshl_add_u64 v[232:233], v[36:37], 0, s[0:1]
	global_load_dwordx4 v[190:193], v[232:233], off
	global_load_dwordx4 v[194:197], v[232:233], off offset:16
	global_load_dwordx4 v[198:201], v[232:233], off offset:2048
	global_load_dwordx4 v[204:207], v[232:233], off offset:2064
	s_waitcnt vmcnt(8)
	v_pk_add_f32 v[174:175], v[174:175], v[208:209]
	v_pk_add_f32 v[176:177], v[176:177], v[210:211]
	v_pk_add_f32 v[178:179], v[178:179], v[212:213]
	v_pk_add_f32 v[180:181], v[180:181], v[214:215]
	v_pk_add_f32 v[182:183], v[182:183], v[216:217]
	v_pk_add_f32 v[184:185], v[184:185], v[218:219]
	v_pk_add_f32 v[186:187], v[186:187], v[220:221]
	v_pk_add_f32 v[188:189], v[188:189], v[222:223]
	s_mov_b64 s[0:1], 0x2801000
	v_lshl_add_u64 v[232:233], v[36:37], 0, s[0:1]
	global_load_dwordx4 v[208:211], v[232:233], off
	global_load_dwordx4 v[212:215], v[232:233], off offset:16
	global_load_dwordx4 v[216:219], v[232:233], off offset:2048
	global_load_dwordx4 v[220:223], v[232:233], off offset:2064
	s_waitcnt vmcnt(8)
	v_pk_add_f32 v[174:175], v[174:175], v[224:225]
	v_pk_add_f32 v[176:177], v[176:177], v[226:227]
	v_pk_add_f32 v[178:179], v[178:179], v[228:229]
	v_pk_add_f32 v[180:181], v[180:181], v[230:231]
	v_pk_add_f32 v[182:183], v[182:183], v[238:239]
	v_pk_add_f32 v[184:185], v[184:185], v[240:241]
	v_pk_add_f32 v[186:187], v[186:187], v[242:243]
	v_pk_add_f32 v[188:189], v[188:189], v[244:245]
	global_load_dwordx4 v[224:227], v[76:77], off
	global_load_dwordx4 v[228:231], v[76:77], off offset:16
	global_load_dwordx4 v[238:241], v[78:79], off
	global_load_dwordx4 v[242:245], v[78:79], off offset:16
	s_waitcnt vmcnt(8)
	v_pk_add_f32 v[174:175], v[174:175], v[190:191]
	v_pk_add_f32 v[176:177], v[176:177], v[192:193]
	v_pk_add_f32 v[178:179], v[178:179], v[194:195]
	v_pk_add_f32 v[180:181], v[180:181], v[196:197]
	v_pk_add_f32 v[182:183], v[182:183], v[198:199]
	v_pk_add_f32 v[184:185], v[184:185], v[200:201]
	v_pk_add_f32 v[186:187], v[186:187], v[204:205]
	v_pk_add_f32 v[188:189], v[188:189], v[206:207]
	s_waitcnt vmcnt(4)
	v_pk_add_f32 v[174:175], v[174:175], v[208:209]
	v_pk_add_f32 v[176:177], v[176:177], v[210:211]
	v_pk_add_f32 v[178:179], v[178:179], v[212:213]
	v_pk_add_f32 v[180:181], v[180:181], v[214:215]
	v_pk_add_f32 v[182:183], v[182:183], v[216:217]
	v_pk_add_f32 v[184:185], v[184:185], v[218:219]
	v_pk_add_f32 v[186:187], v[186:187], v[220:221]
	v_pk_add_f32 v[188:189], v[188:189], v[222:223]
	s_waitcnt vmcnt(0)
	v_pk_fma_f32 v[44:45], v[174:175], v[224:225], v[44:45]
	v_pk_fma_f32 v[46:47], v[176:177], v[226:227], v[46:47]
	v_pk_fma_f32 v[42:43], v[178:179], v[228:229], v[42:43]
	v_pk_fma_f32 v[48:49], v[180:181], v[230:231], v[48:49]
	v_pk_fma_f32 v[38:39], v[182:183], v[238:239], v[38:39]
	v_pk_fma_f32 v[40:41], v[184:185], v[240:241], v[40:41]
	v_pk_fma_f32 v[32:33], v[186:187], v[242:243], v[32:33]
	v_pk_fma_f32 v[34:35], v[188:189], v[244:245], v[34:35]

.LBB0_1055:
	s_add_i32 s0, s75, s8
	s_cmpk_lt_i32 s0, 0x4200
	s_cselect_b32 s0, s0, s8
	s_ashr_i32 s1, s0, 31
	s_lshl_b64 s[0:1], s[0:1], 12
	v_lshl_add_u64 v[32:33], v[80:81], 0, s[0:1]
	global_load_dwordx4 v[46:49], v[32:33], off
	global_load_dwordx4 v[42:45], v[32:33], off offset:1024
	global_load_dwordx4 v[38:41], v[32:33], off offset:2048
	global_load_dwordx4 v[34:37], v[32:33], off offset:3072
	s_waitcnt vmcnt(4)
	s_andn2_b64 vcc, exec, s[14:15]
	s_cbranch_vccnz .LBB0_1045
	v_cvt_f32_f16_sdwa v167, v62 dst_sel:DWORD dst_unused:UNUSED_PAD src0_sel:WORD_1
	v_cvt_f32_f16_e32 v166, v62
	v_cvt_f32_f16_sdwa v163, v63 dst_sel:DWORD dst_unused:UNUSED_PAD src0_sel:WORD_1
	v_cvt_f32_f16_e32 v162, v63
	v_cvt_f32_f16_sdwa v161, v64 dst_sel:DWORD dst_unused:UNUSED_PAD src0_sel:WORD_1
	v_cvt_f32_f16_e32 v160, v64
	v_cvt_f32_f16_sdwa v165, v65 dst_sel:DWORD dst_unused:UNUSED_PAD src0_sel:WORD_1
	v_cvt_f32_f16_e32 v164, v65
	v_cvt_f32_f16_sdwa v155, v58 dst_sel:DWORD dst_unused:UNUSED_PAD src0_sel:WORD_1
	v_cvt_f32_f16_e32 v154, v58
	v_cvt_f32_f16_sdwa v157, v59 dst_sel:DWORD dst_unused:UNUSED_PAD src0_sel:WORD_1
	v_cvt_f32_f16_e32 v156, v59
	v_cvt_f32_f16_sdwa v153, v60 dst_sel:DWORD dst_unused:UNUSED_PAD src0_sel:WORD_1
	v_cvt_f32_f16_e32 v152, v60
	v_cvt_f32_f16_sdwa v159, v61 dst_sel:DWORD dst_unused:UNUSED_PAD src0_sel:WORD_1
	v_cvt_f32_f16_e32 v158, v61
	v_cvt_f32_f16_sdwa v61, v54 dst_sel:DWORD dst_unused:UNUSED_PAD src0_sel:WORD_1
	v_cvt_f32_f16_e32 v60, v54
	v_cvt_f32_f16_sdwa v63, v55 dst_sel:DWORD dst_unused:UNUSED_PAD src0_sel:WORD_1
	v_cvt_f32_f16_e32 v62, v55
	v_cvt_f32_f16_sdwa v59, v56 dst_sel:DWORD dst_unused:UNUSED_PAD src0_sel:WORD_1
	v_cvt_f32_f16_e32 v58, v56
	v_cvt_f32_f16_sdwa v65, v57 dst_sel:DWORD dst_unused:UNUSED_PAD src0_sel:WORD_1
	v_cvt_f32_f16_e32 v64, v57
	v_cvt_f32_f16_sdwa v55, v50 dst_sel:DWORD dst_unused:UNUSED_PAD src0_sel:WORD_1
	v_cvt_f32_f16_e32 v54, v50
	v_cvt_f32_f16_sdwa v57, v51 dst_sel:DWORD dst_unused:UNUSED_PAD src0_sel:WORD_1
	v_cvt_f32_f16_e32 v56, v51
	v_cvt_f32_f16_sdwa v33, v52 dst_sel:DWORD dst_unused:UNUSED_PAD src0_sel:WORD_1
	v_cvt_f32_f16_e32 v32, v52
	v_cvt_f32_f16_sdwa v51, v53 dst_sel:DWORD dst_unused:UNUSED_PAD src0_sel:WORD_1
	v_cvt_f32_f16_e32 v50, v53
	s_cmpk_gt_i32 s16, 0x3fff
	s_cselect_b64 s[2:3], -1, 0
	s_cmpk_lt_i32 s16, 0x4000
	s_cbranch_scc1 .LBB0_1058
	s_add_i32 s86, s16, 0xffffc000
	s_lshl_b64 s[0:1], s[86:87], 13
	v_lshl_add_u64 v[52:53], v[82:83], 0, s[0:1]
	global_load_dwordx4 v[190:193], v[52:53], off
	global_load_dwordx4 v[194:197], v[52:53], off offset:16
	global_load_dwordx4 v[198:201], v[52:53], off offset:2048
	global_load_dwordx4 v[204:207], v[52:53], off offset:2064
	s_mov_b64 s[0:1], 0x400000
	v_lshl_add_u64 v[232:233], v[52:53], 0, s[0:1]
	global_load_dwordx4 v[208:211], v[232:233], off
	global_load_dwordx4 v[212:215], v[232:233], off offset:16
	global_load_dwordx4 v[216:219], v[232:233], off offset:2048
	global_load_dwordx4 v[220:223], v[232:233], off offset:2064
	s_mov_b64 s[0:1], 0x800000
	v_lshl_add_u64 v[232:233], v[52:53], 0, s[0:1]
	global_load_dwordx4 v[224:227], v[232:233], off
	global_load_dwordx4 v[228:231], v[232:233], off offset:16
	global_load_dwordx4 v[238:241], v[232:233], off offset:2048
	global_load_dwordx4 v[242:245], v[232:233], off offset:2064
	s_waitcnt vmcnt(8)
	v_mov_b64_e32 v[174:175], v[190:191]
	v_mov_b64_e32 v[176:177], v[192:193]
	v_mov_b64_e32 v[178:179], v[194:195]
	v_mov_b64_e32 v[180:181], v[196:197]
	v_mov_b64_e32 v[182:183], v[198:199]
	v_mov_b64_e32 v[184:185], v[200:201]
	v_mov_b64_e32 v[186:187], v[204:205]
	v_mov_b64_e32 v[188:189], v[206:207]
	s_mov_b64 s[0:1], 0xc00000
	v_lshl_add_u64 v[232:233], v[52:53], 0, s[0:1]
	global_load_dwordx4 v[190:193], v[232:233], off
	global_load_dwordx4 v[194:197], v[232:233], off offset:16
	global_load_dwordx4 v[198:201], v[232:233], off offset:2048
	global_load_dwordx4 v[204:207], v[232:233], off offset:2064
	s_waitcnt vmcnt(8)
	v_pk_add_f32 v[174:175], v[174:175], v[208:209]
	v_pk_add_f32 v[176:177], v[176:177], v[210:211]
	v_pk_add_f32 v[178:179], v[178:179], v[212:213]
	v_pk_add_f32 v[180:181], v[180:181], v[214:215]
	v_pk_add_f32 v[182:183], v[182:183], v[216:217]
	v_pk_add_f32 v[184:185], v[184:185], v[218:219]
	v_pk_add_f32 v[186:187], v[186:187], v[220:221]
	v_pk_add_f32 v[188:189], v[188:189], v[222:223]
	s_mov_b64 s[0:1], 0x1000000
	v_lshl_add_u64 v[232:233], v[52:53], 0, s[0:1]
	global_load_dwordx4 v[208:211], v[232:233], off
	global_load_dwordx4 v[212:215], v[232:233], off offset:16
	global_load_dwordx4 v[216:219], v[232:233], off offset:2048
	global_load_dwordx4 v[220:223], v[232:233], off offset:2064
	s_waitcnt vmcnt(8)
	v_pk_add_f32 v[174:175], v[174:175], v[224:225]
	v_pk_add_f32 v[176:177], v[176:177], v[226:227]
	v_pk_add_f32 v[178:179], v[178:179], v[228:229]
	v_pk_add_f32 v[180:181], v[180:181], v[230:231]
	v_pk_add_f32 v[182:183], v[182:183], v[238:239]
	v_pk_add_f32 v[184:185], v[184:185], v[240:241]
	v_pk_add_f32 v[186:187], v[186:187], v[242:243]
	v_pk_add_f32 v[188:189], v[188:189], v[244:245]
	s_mov_b64 s[0:1], 0x1400000
	v_lshl_add_u64 v[232:233], v[52:53], 0, s[0:1]
	global_load_dwordx4 v[224:227], v[232:233], off
	global_load_dwordx4 v[228:231], v[232:233], off offset:16
	global_load_dwordx4 v[238:241], v[232:233], off offset:2048
	global_load_dwordx4 v[242:245], v[232:233], off offset:2064
	s_waitcnt vmcnt(8)
	v_pk_add_f32 v[174:175], v[174:175], v[190:191]
	v_pk_add_f32 v[176:177], v[176:177], v[192:193]
	v_pk_add_f32 v[178:179], v[178:179], v[194:195]
	v_pk_add_f32 v[180:181], v[180:181], v[196:197]
	v_pk_add_f32 v[182:183], v[182:183], v[198:199]
	v_pk_add_f32 v[184:185], v[184:185], v[200:201]
	v_pk_add_f32 v[186:187], v[186:187], v[204:205]
	v_pk_add_f32 v[188:189], v[188:189], v[206:207]
	s_mov_b64 s[0:1], 0x1800000
	v_lshl_add_u64 v[232:233], v[52:53], 0, s[0:1]
	global_load_dwordx4 v[190:193], v[232:233], off
	global_load_dwordx4 v[194:197], v[232:233], off offset:16
	global_load_dwordx4 v[198:201], v[232:233], off offset:2048
	global_load_dwordx4 v[204:207], v[232:233], off offset:2064
	s_waitcnt vmcnt(8)
	v_pk_add_f32 v[174:175], v[174:175], v[208:209]
	v_pk_add_f32 v[176:177], v[176:177], v[210:211]
	v_pk_add_f32 v[178:179], v[178:179], v[212:213]
	v_pk_add_f32 v[180:181], v[180:181], v[214:215]
	v_pk_add_f32 v[182:183], v[182:183], v[216:217]
	v_pk_add_f32 v[184:185], v[184:185], v[218:219]
	v_pk_add_f32 v[186:187], v[186:187], v[220:221]
	v_pk_add_f32 v[188:189], v[188:189], v[222:223]
	s_mov_b64 s[0:1], 0x1c00000
	v_lshl_add_u64 v[232:233], v[52:53], 0, s[0:1]
	global_load_dwordx4 v[208:211], v[232:233], off
	global_load_dwordx4 v[212:215], v[232:233], off offset:16
	global_load_dwordx4 v[216:219], v[232:233], off offset:2048
	global_load_dwordx4 v[220:223], v[232:233], off offset:2064
	s_waitcnt vmcnt(8)
	v_pk_add_f32 v[174:175], v[174:175], v[224:225]
	v_pk_add_f32 v[176:177], v[176:177], v[226:227]
	v_pk_add_f32 v[178:179], v[178:179], v[228:229]
	v_pk_add_f32 v[180:181], v[180:181], v[230:231]
	v_pk_add_f32 v[182:183], v[182:183], v[238:239]
	v_pk_add_f32 v[184:185], v[184:185], v[240:241]
	v_pk_add_f32 v[186:187], v[186:187], v[242:243]
	v_pk_add_f32 v[188:189], v[188:189], v[244:245]
	s_mov_b64 s[0:1], 0x2000000
	v_lshl_add_u64 v[232:233], v[52:53], 0, s[0:1]
	global_load_dwordx4 v[224:227], v[232:233], off
	global_load_dwordx4 v[228:231], v[232:233], off offset:16
	global_load_dwordx4 v[238:241], v[232:233], off offset:2048
	global_load_dwordx4 v[242:245], v[232:233], off offset:2064
	s_waitcnt vmcnt(8)
	v_pk_add_f32 v[174:175], v[174:175], v[190:191]
	v_pk_add_f32 v[176:177], v[176:177], v[192:193]
	v_pk_add_f32 v[178:179], v[178:179], v[194:195]
	v_pk_add_f32 v[180:181], v[180:181], v[196:197]
	v_pk_add_f32 v[182:183], v[182:183], v[198:199]
	v_pk_add_f32 v[184:185], v[184:185], v[200:201]
	v_pk_add_f32 v[186:187], v[186:187], v[204:205]
	v_pk_add_f32 v[188:189], v[188:189], v[206:207]
	s_mov_b64 s[0:1], 0x2400000
	v_lshl_add_u64 v[232:233], v[52:53], 0, s[0:1]
	global_load_dwordx4 v[190:193], v[232:233], off
	global_load_dwordx4 v[194:197], v[232:233], off offset:16
	global_load_dwordx4 v[198:201], v[232:233], off offset:2048
	global_load_dwordx4 v[204:207], v[232:233], off offset:2064
	s_waitcnt vmcnt(8)
	v_pk_add_f32 v[174:175], v[174:175], v[208:209]
	v_pk_add_f32 v[176:177], v[176:177], v[210:211]
	v_pk_add_f32 v[178:179], v[178:179], v[212:213]
	v_pk_add_f32 v[180:181], v[180:181], v[214:215]
	v_pk_add_f32 v[182:183], v[182:183], v[216:217]
	v_pk_add_f32 v[184:185], v[184:185], v[218:219]
	v_pk_add_f32 v[186:187], v[186:187], v[220:221]
	v_pk_add_f32 v[188:189], v[188:189], v[222:223]
	s_mov_b64 s[0:1], 0x2800000
	v_lshl_add_u64 v[232:233], v[52:53], 0, s[0:1]
	global_load_dwordx4 v[208:211], v[232:233], off
	global_load_dwordx4 v[212:215], v[232:233], off offset:16
	global_load_dwordx4 v[216:219], v[232:233], off offset:2048
	global_load_dwordx4 v[220:223], v[232:233], off offset:2064
	s_waitcnt vmcnt(8)
	v_pk_add_f32 v[174:175], v[174:175], v[224:225]
	v_pk_add_f32 v[176:177], v[176:177], v[226:227]
	v_pk_add_f32 v[178:179], v[178:179], v[228:229]
	v_pk_add_f32 v[180:181], v[180:181], v[230:231]
	v_pk_add_f32 v[182:183], v[182:183], v[238:239]
	v_pk_add_f32 v[184:185], v[184:185], v[240:241]
	v_pk_add_f32 v[186:187], v[186:187], v[242:243]
	v_pk_add_f32 v[188:189], v[188:189], v[244:245]
	global_load_dwordx4 v[224:227], v[74:75], off
	global_load_dwordx4 v[228:231], v[74:75], off offset:16
	global_load_dwordx4 v[238:241], v[74:75], off offset:2048
	global_load_dwordx4 v[242:245], v[74:75], off offset:2064
	s_waitcnt vmcnt(8)
	v_pk_add_f32 v[174:175], v[174:175], v[190:191]
	v_pk_add_f32 v[176:177], v[176:177], v[192:193]
	v_pk_add_f32 v[178:179], v[178:179], v[194:195]
	v_pk_add_f32 v[180:181], v[180:181], v[196:197]
	v_pk_add_f32 v[182:183], v[182:183], v[198:199]
	v_pk_add_f32 v[184:185], v[184:185], v[200:201]
	v_pk_add_f32 v[186:187], v[186:187], v[204:205]
	v_pk_add_f32 v[188:189], v[188:189], v[206:207]
	s_mov_b64 s[0:1], 0x1000
	v_lshl_add_u64 v[232:233], v[52:53], 0, s[0:1]
	global_load_dwordx4 v[190:193], v[232:233], off
	global_load_dwordx4 v[194:197], v[232:233], off offset:16
	global_load_dwordx4 v[198:201], v[232:233], off offset:2048
	global_load_dwordx4 v[204:207], v[232:233], off offset:2064
	s_waitcnt vmcnt(8)
	v_pk_add_f32 v[174:175], v[174:175], v[208:209]
	v_pk_add_f32 v[176:177], v[176:177], v[210:211]
	v_pk_add_f32 v[178:179], v[178:179], v[212:213]
	v_pk_add_f32 v[180:181], v[180:181], v[214:215]
	v_pk_add_f32 v[182:183], v[182:183], v[216:217]
	v_pk_add_f32 v[184:185], v[184:185], v[218:219]
	v_pk_add_f32 v[186:187], v[186:187], v[220:221]
	v_pk_add_f32 v[188:189], v[188:189], v[222:223]
	s_mov_b64 s[0:1], 0x401000
	v_lshl_add_u64 v[232:233], v[52:53], 0, s[0:1]
	global_load_dwordx4 v[208:211], v[232:233], off
	global_load_dwordx4 v[212:215], v[232:233], off offset:16
	global_load_dwordx4 v[216:219], v[232:233], off offset:2048
	global_load_dwordx4 v[220:223], v[232:233], off offset:2064
	s_waitcnt vmcnt(8)
	v_pk_fma_f32 v[166:167], v[174:175], v[224:225], v[166:167]
	v_pk_fma_f32 v[162:163], v[176:177], v[226:227], v[162:163]
	v_pk_fma_f32 v[160:161], v[178:179], v[228:229], v[160:161]
	v_pk_fma_f32 v[164:165], v[180:181], v[230:231], v[164:165]
	v_pk_fma_f32 v[154:155], v[182:183], v[238:239], v[154:155]
	v_pk_fma_f32 v[156:157], v[184:185], v[240:241], v[156:157]
	v_pk_fma_f32 v[152:153], v[186:187], v[242:243], v[152:153]
	v_pk_fma_f32 v[158:159], v[188:189], v[244:245], v[158:159]
	s_mov_b64 s[0:1], 0x801000
	v_lshl_add_u64 v[232:233], v[52:53], 0, s[0:1]
	global_load_dwordx4 v[224:227], v[232:233], off
	global_load_dwordx4 v[228:231], v[232:233], off offset:16
	global_load_dwordx4 v[238:241], v[232:233], off offset:2048
	global_load_dwordx4 v[242:245], v[232:233], off offset:2064
	s_waitcnt vmcnt(8)
	v_mov_b64_e32 v[174:175], v[190:191]
	v_mov_b64_e32 v[176:177], v[192:193]
	v_mov_b64_e32 v[178:179], v[194:195]
	v_mov_b64_e32 v[180:181], v[196:197]
	v_mov_b64_e32 v[182:183], v[198:199]
	v_mov_b64_e32 v[184:185], v[200:201]
	v_mov_b64_e32 v[186:187], v[204:205]
	v_mov_b64_e32 v[188:189], v[206:207]
	s_mov_b64 s[0:1], 0xc01000
	v_lshl_add_u64 v[232:233], v[52:53], 0, s[0:1]
	global_load_dwordx4 v[190:193], v[232:233], off
	global_load_dwordx4 v[194:197], v[232:233], off offset:16
	global_load_dwordx4 v[198:201], v[232:233], off offset:2048
	global_load_dwordx4 v[204:207], v[232:233], off offset:2064
	s_waitcnt vmcnt(8)
	v_pk_add_f32 v[174:175], v[174:175], v[208:209]
	v_pk_add_f32 v[176:177], v[176:177], v[210:211]
	v_pk_add_f32 v[178:179], v[178:179], v[212:213]
	v_pk_add_f32 v[180:181], v[180:181], v[214:215]
	v_pk_add_f32 v[182:183], v[182:183], v[216:217]
	v_pk_add_f32 v[184:185], v[184:185], v[218:219]
	v_pk_add_f32 v[186:187], v[186:187], v[220:221]
	v_pk_add_f32 v[188:189], v[188:189], v[222:223]
	s_mov_b64 s[0:1], 0x1001000
	v_lshl_add_u64 v[232:233], v[52:53], 0, s[0:1]
	global_load_dwordx4 v[208:211], v[232:233], off
	global_load_dwordx4 v[212:215], v[232:233], off offset:16
	global_load_dwordx4 v[216:219], v[232:233], off offset:2048
	global_load_dwordx4 v[220:223], v[232:233], off offset:2064
	s_waitcnt vmcnt(8)
	v_pk_add_f32 v[174:175], v[174:175], v[224:225]
	v_pk_add_f32 v[176:177], v[176:177], v[226:227]
	v_pk_add_f32 v[178:179], v[178:179], v[228:229]
	v_pk_add_f32 v[180:181], v[180:181], v[230:231]
	v_pk_add_f32 v[182:183], v[182:183], v[238:239]
	v_pk_add_f32 v[184:185], v[184:185], v[240:241]
	v_pk_add_f32 v[186:187], v[186:187], v[242:243]
	v_pk_add_f32 v[188:189], v[188:189], v[244:245]
	s_mov_b64 s[0:1], 0x1401000
	v_lshl_add_u64 v[232:233], v[52:53], 0, s[0:1]
	global_load_dwordx4 v[224:227], v[232:233], off
	global_load_dwordx4 v[228:231], v[232:233], off offset:16
	global_load_dwordx4 v[238:241], v[232:233], off offset:2048
	global_load_dwordx4 v[242:245], v[232:233], off offset:2064
	s_waitcnt vmcnt(8)
	v_pk_add_f32 v[174:175], v[174:175], v[190:191]
	v_pk_add_f32 v[176:177], v[176:177], v[192:193]
	v_pk_add_f32 v[178:179], v[178:179], v[194:195]
	v_pk_add_f32 v[180:181], v[180:181], v[196:197]
	v_pk_add_f32 v[182:183], v[182:183], v[198:199]
	v_pk_add_f32 v[184:185], v[184:185], v[200:201]
	v_pk_add_f32 v[186:187], v[186:187], v[204:205]
	v_pk_add_f32 v[188:189], v[188:189], v[206:207]
	s_mov_b64 s[0:1], 0x1801000
	v_lshl_add_u64 v[232:233], v[52:53], 0, s[0:1]
	global_load_dwordx4 v[190:193], v[232:233], off
	global_load_dwordx4 v[194:197], v[232:233], off offset:16
	global_load_dwordx4 v[198:201], v[232:233], off offset:2048
	global_load_dwordx4 v[204:207], v[232:233], off offset:2064
	s_waitcnt vmcnt(8)
	v_pk_add_f32 v[174:175], v[174:175], v[208:209]
	v_pk_add_f32 v[176:177], v[176:177], v[210:211]
	v_pk_add_f32 v[178:179], v[178:179], v[212:213]
	v_pk_add_f32 v[180:181], v[180:181], v[214:215]
	v_pk_add_f32 v[182:183], v[182:183], v[216:217]
	v_pk_add_f32 v[184:185], v[184:185], v[218:219]
	v_pk_add_f32 v[186:187], v[186:187], v[220:221]
	v_pk_add_f32 v[188:189], v[188:189], v[222:223]
	s_mov_b64 s[0:1], 0x1c01000
	v_lshl_add_u64 v[232:233], v[52:53], 0, s[0:1]
	global_load_dwordx4 v[208:211], v[232:233], off
	global_load_dwordx4 v[212:215], v[232:233], off offset:16
	global_load_dwordx4 v[216:219], v[232:233], off offset:2048
	global_load_dwordx4 v[220:223], v[232:233], off offset:2064
	s_waitcnt vmcnt(8)
	v_pk_add_f32 v[174:175], v[174:175], v[224:225]
	v_pk_add_f32 v[176:177], v[176:177], v[226:227]
	v_pk_add_f32 v[178:179], v[178:179], v[228:229]
	v_pk_add_f32 v[180:181], v[180:181], v[230:231]
	v_pk_add_f32 v[182:183], v[182:183], v[238:239]
	v_pk_add_f32 v[184:185], v[184:185], v[240:241]
	v_pk_add_f32 v[186:187], v[186:187], v[242:243]
	v_pk_add_f32 v[188:189], v[188:189], v[244:245]
	s_mov_b64 s[0:1], 0x2001000
	v_lshl_add_u64 v[232:233], v[52:53], 0, s[0:1]
	global_load_dwordx4 v[224:227], v[232:233], off
	global_load_dwordx4 v[228:231], v[232:233], off offset:16
	global_load_dwordx4 v[238:241], v[232:233], off offset:2048
	global_load_dwordx4 v[242:245], v[232:233], off offset:2064
	s_waitcnt vmcnt(8)
	v_pk_add_f32 v[174:175], v[174:175], v[190:191]
	v_pk_add_f32 v[176:177], v[176:177], v[192:193]
	v_pk_add_f32 v[178:179], v[178:179], v[194:195]
	v_pk_add_f32 v[180:181], v[180:181], v[196:197]
	v_pk_add_f32 v[182:183], v[182:183], v[198:199]
	v_pk_add_f32 v[184:185], v[184:185], v[200:201]
	v_pk_add_f32 v[186:187], v[186:187], v[204:205]
	v_pk_add_f32 v[188:189], v[188:189], v[206:207]
	s_mov_b64 s[0:1], 0x2401000
	v_lshl_add_u64 v[232:233], v[52:53], 0, s[0:1]
	global_load_dwordx4 v[190:193], v[232:233], off
	global_load_dwordx4 v[194:197], v[232:233], off offset:16
	global_load_dwordx4 v[198:201], v[232:233], off offset:2048
	global_load_dwordx4 v[204:207], v[232:233], off offset:2064
	s_waitcnt vmcnt(8)
	v_pk_add_f32 v[174:175], v[174:175], v[208:209]
	v_pk_add_f32 v[176:177], v[176:177], v[210:211]
	v_pk_add_f32 v[178:179], v[178:179], v[212:213]
	v_pk_add_f32 v[180:181], v[180:181], v[214:215]
	v_pk_add_f32 v[182:183], v[182:183], v[216:217]
	v_pk_add_f32 v[184:185], v[184:185], v[218:219]
	v_pk_add_f32 v[186:187], v[186:187], v[220:221]
	v_pk_add_f32 v[188:189], v[188:189], v[222:223]
	s_mov_b64 s[0:1], 0x2801000
	v_lshl_add_u64 v[232:233], v[52:53], 0, s[0:1]
	global_load_dwordx4 v[208:211], v[232:233], off
	global_load_dwordx4 v[212:215], v[232:233], off offset:16
	global_load_dwordx4 v[216:219], v[232:233], off offset:2048
	global_load_dwordx4 v[220:223], v[232:233], off offset:2064
	s_waitcnt vmcnt(8)
	v_pk_add_f32 v[174:175], v[174:175], v[224:225]
	v_pk_add_f32 v[176:177], v[176:177], v[226:227]
	v_pk_add_f32 v[178:179], v[178:179], v[228:229]
	v_pk_add_f32 v[180:181], v[180:181], v[230:231]
	v_pk_add_f32 v[182:183], v[182:183], v[238:239]
	v_pk_add_f32 v[184:185], v[184:185], v[240:241]
	v_pk_add_f32 v[186:187], v[186:187], v[242:243]
	v_pk_add_f32 v[188:189], v[188:189], v[244:245]
	global_load_dwordx4 v[224:227], v[76:77], off
	global_load_dwordx4 v[228:231], v[76:77], off offset:16
	global_load_dwordx4 v[238:241], v[78:79], off
	global_load_dwordx4 v[242:245], v[78:79], off offset:16
	s_waitcnt vmcnt(8)
	v_pk_add_f32 v[174:175], v[174:175], v[190:191]
	v_pk_add_f32 v[176:177], v[176:177], v[192:193]
	v_pk_add_f32 v[178:179], v[178:179], v[194:195]
	v_pk_add_f32 v[180:181], v[180:181], v[196:197]
	v_pk_add_f32 v[182:183], v[182:183], v[198:199]
	v_pk_add_f32 v[184:185], v[184:185], v[200:201]
	v_pk_add_f32 v[186:187], v[186:187], v[204:205]
	v_pk_add_f32 v[188:189], v[188:189], v[206:207]
	s_waitcnt vmcnt(4)
	v_pk_add_f32 v[174:175], v[174:175], v[208:209]
	v_pk_add_f32 v[176:177], v[176:177], v[210:211]
	v_pk_add_f32 v[178:179], v[178:179], v[212:213]
	v_pk_add_f32 v[180:181], v[180:181], v[214:215]
	v_pk_add_f32 v[182:183], v[182:183], v[216:217]
	v_pk_add_f32 v[184:185], v[184:185], v[218:219]
	v_pk_add_f32 v[186:187], v[186:187], v[220:221]
	v_pk_add_f32 v[188:189], v[188:189], v[222:223]
	s_waitcnt vmcnt(0)
	v_pk_fma_f32 v[60:61], v[174:175], v[224:225], v[60:61]
	v_pk_fma_f32 v[62:63], v[176:177], v[226:227], v[62:63]
	v_pk_fma_f32 v[58:59], v[178:179], v[228:229], v[58:59]
	v_pk_fma_f32 v[64:65], v[180:181], v[230:231], v[64:65]
	v_pk_fma_f32 v[54:55], v[182:183], v[238:239], v[54:55]
	v_pk_fma_f32 v[56:57], v[184:185], v[240:241], v[56:57]
	v_pk_fma_f32 v[32:33], v[186:187], v[242:243], v[32:33]
	v_pk_fma_f32 v[50:51], v[188:189], v[244:245], v[50:51]

.LBB0_1806:
	s_add_i32 s14, s4, s94
	s_cmpk_lt_i32 s14, 0x4200
	s_cselect_b64 s[8:9], -1, 0
	s_and_b64 s[0:1], s[8:9], exec
	s_cselect_b32 s6, s14, s4
	s_ashr_i32 s7, s6, 31
	s_lshl_b64 s[0:1], s[6:7], 12
	v_lshl_add_u64 v[32:33], v[80:81], 0, s[0:1]
	s_waitcnt vmcnt(0)
	global_load_dwordx4 v[62:65], v[32:33], off
	global_load_dwordx4 v[58:61], v[32:33], off offset:1024
	global_load_dwordx4 v[54:57], v[32:33], off offset:2048
	global_load_dwordx4 v[50:53], v[32:33], off offset:3072
	v_cvt_f32_f16_sdwa v167, v46 dst_sel:DWORD dst_unused:UNUSED_PAD src0_sel:WORD_1
	v_cvt_f32_f16_e32 v166, v46
	v_cvt_f32_f16_sdwa v163, v47 dst_sel:DWORD dst_unused:UNUSED_PAD src0_sel:WORD_1
	v_cvt_f32_f16_e32 v162, v47
	v_cvt_f32_f16_sdwa v161, v48 dst_sel:DWORD dst_unused:UNUSED_PAD src0_sel:WORD_1
	v_cvt_f32_f16_e32 v160, v48
	v_cvt_f32_f16_sdwa v165, v49 dst_sel:DWORD dst_unused:UNUSED_PAD src0_sel:WORD_1
	v_cvt_f32_f16_e32 v164, v49
	v_cvt_f32_f16_sdwa v155, v42 dst_sel:DWORD dst_unused:UNUSED_PAD src0_sel:WORD_1
	v_cvt_f32_f16_e32 v154, v42
	v_cvt_f32_f16_sdwa v157, v43 dst_sel:DWORD dst_unused:UNUSED_PAD src0_sel:WORD_1
	v_cvt_f32_f16_e32 v156, v43
	v_cvt_f32_f16_sdwa v153, v44 dst_sel:DWORD dst_unused:UNUSED_PAD src0_sel:WORD_1
	v_cvt_f32_f16_e32 v152, v44
	v_cvt_f32_f16_sdwa v159, v45 dst_sel:DWORD dst_unused:UNUSED_PAD src0_sel:WORD_1
	v_cvt_f32_f16_e32 v158, v45
	v_cvt_f32_f16_sdwa v45, v38 dst_sel:DWORD dst_unused:UNUSED_PAD src0_sel:WORD_1
	v_cvt_f32_f16_e32 v44, v38
	v_cvt_f32_f16_sdwa v47, v39 dst_sel:DWORD dst_unused:UNUSED_PAD src0_sel:WORD_1
	v_cvt_f32_f16_e32 v46, v39
	v_cvt_f32_f16_sdwa v43, v40 dst_sel:DWORD dst_unused:UNUSED_PAD src0_sel:WORD_1
	v_cvt_f32_f16_e32 v42, v40
	v_cvt_f32_f16_sdwa v49, v41 dst_sel:DWORD dst_unused:UNUSED_PAD src0_sel:WORD_1
	v_cvt_f32_f16_e32 v48, v41
	v_cvt_f32_f16_sdwa v39, v34 dst_sel:DWORD dst_unused:UNUSED_PAD src0_sel:WORD_1
	v_cvt_f32_f16_e32 v38, v34
	v_cvt_f32_f16_sdwa v41, v35 dst_sel:DWORD dst_unused:UNUSED_PAD src0_sel:WORD_1
	v_cvt_f32_f16_e32 v40, v35
	v_cvt_f32_f16_sdwa v33, v36 dst_sel:DWORD dst_unused:UNUSED_PAD src0_sel:WORD_1
	v_cvt_f32_f16_e32 v32, v36
	v_cvt_f32_f16_sdwa v35, v37 dst_sel:DWORD dst_unused:UNUSED_PAD src0_sel:WORD_1
	v_cvt_f32_f16_e32 v34, v37
	s_cmpk_gt_i32 s4, 0x3fff
	s_cselect_b64 s[2:3], -1, 0
	s_cmpk_lt_i32 s4, 0x4000
	s_cbranch_scc1 .LBB0_1808
	s_add_i32 s86, s4, 0xffffc000
	s_lshl_b64 s[0:1], s[86:87], 13
	v_lshl_add_u64 v[36:37], v[82:83], 0, s[0:1]
	global_load_dwordx4 v[190:193], v[36:37], off
	global_load_dwordx4 v[194:197], v[36:37], off offset:16
	global_load_dwordx4 v[198:201], v[36:37], off offset:2048
	global_load_dwordx4 v[204:207], v[36:37], off offset:2064
	s_mov_b64 s[0:1], 0x400000
	v_lshl_add_u64 v[232:233], v[36:37], 0, s[0:1]
	global_load_dwordx4 v[208:211], v[232:233], off
	global_load_dwordx4 v[212:215], v[232:233], off offset:16
	global_load_dwordx4 v[216:219], v[232:233], off offset:2048
	global_load_dwordx4 v[220:223], v[232:233], off offset:2064
	s_mov_b64 s[0:1], 0x800000
	v_lshl_add_u64 v[232:233], v[36:37], 0, s[0:1]
	global_load_dwordx4 v[224:227], v[232:233], off
	global_load_dwordx4 v[228:231], v[232:233], off offset:16
	global_load_dwordx4 v[238:241], v[232:233], off offset:2048
	global_load_dwordx4 v[242:245], v[232:233], off offset:2064
	s_waitcnt vmcnt(8)
	v_mov_b64_e32 v[174:175], v[190:191]
	v_mov_b64_e32 v[176:177], v[192:193]
	v_mov_b64_e32 v[178:179], v[194:195]
	v_mov_b64_e32 v[180:181], v[196:197]
	v_mov_b64_e32 v[182:183], v[198:199]
	v_mov_b64_e32 v[184:185], v[200:201]
	v_mov_b64_e32 v[186:187], v[204:205]
	v_mov_b64_e32 v[188:189], v[206:207]
	s_mov_b64 s[0:1], 0xc00000
	v_lshl_add_u64 v[232:233], v[36:37], 0, s[0:1]
	global_load_dwordx4 v[190:193], v[232:233], off
	global_load_dwordx4 v[194:197], v[232:233], off offset:16
	global_load_dwordx4 v[198:201], v[232:233], off offset:2048
	global_load_dwordx4 v[204:207], v[232:233], off offset:2064
	s_waitcnt vmcnt(8)
	v_pk_add_f32 v[174:175], v[174:175], v[208:209]
	v_pk_add_f32 v[176:177], v[176:177], v[210:211]
	v_pk_add_f32 v[178:179], v[178:179], v[212:213]
	v_pk_add_f32 v[180:181], v[180:181], v[214:215]
	v_pk_add_f32 v[182:183], v[182:183], v[216:217]
	v_pk_add_f32 v[184:185], v[184:185], v[218:219]
	v_pk_add_f32 v[186:187], v[186:187], v[220:221]
	v_pk_add_f32 v[188:189], v[188:189], v[222:223]
	s_mov_b64 s[0:1], 0x1000000
	v_lshl_add_u64 v[232:233], v[36:37], 0, s[0:1]
	global_load_dwordx4 v[208:211], v[232:233], off
	global_load_dwordx4 v[212:215], v[232:233], off offset:16
	global_load_dwordx4 v[216:219], v[232:233], off offset:2048
	global_load_dwordx4 v[220:223], v[232:233], off offset:2064
	s_waitcnt vmcnt(8)
	v_pk_add_f32 v[174:175], v[174:175], v[224:225]
	v_pk_add_f32 v[176:177], v[176:177], v[226:227]
	v_pk_add_f32 v[178:179], v[178:179], v[228:229]
	v_pk_add_f32 v[180:181], v[180:181], v[230:231]
	v_pk_add_f32 v[182:183], v[182:183], v[238:239]
	v_pk_add_f32 v[184:185], v[184:185], v[240:241]
	v_pk_add_f32 v[186:187], v[186:187], v[242:243]
	v_pk_add_f32 v[188:189], v[188:189], v[244:245]
	s_mov_b64 s[0:1], 0x1400000
	v_lshl_add_u64 v[232:233], v[36:37], 0, s[0:1]
	global_load_dwordx4 v[224:227], v[232:233], off
	global_load_dwordx4 v[228:231], v[232:233], off offset:16
	global_load_dwordx4 v[238:241], v[232:233], off offset:2048
	global_load_dwordx4 v[242:245], v[232:233], off offset:2064
	s_waitcnt vmcnt(8)
	v_pk_add_f32 v[174:175], v[174:175], v[190:191]
	v_pk_add_f32 v[176:177], v[176:177], v[192:193]
	v_pk_add_f32 v[178:179], v[178:179], v[194:195]
	v_pk_add_f32 v[180:181], v[180:181], v[196:197]
	v_pk_add_f32 v[182:183], v[182:183], v[198:199]
	v_pk_add_f32 v[184:185], v[184:185], v[200:201]
	v_pk_add_f32 v[186:187], v[186:187], v[204:205]
	v_pk_add_f32 v[188:189], v[188:189], v[206:207]
	s_mov_b64 s[0:1], 0x1800000
	v_lshl_add_u64 v[232:233], v[36:37], 0, s[0:1]
	global_load_dwordx4 v[190:193], v[232:233], off
	global_load_dwordx4 v[194:197], v[232:233], off offset:16
	global_load_dwordx4 v[198:201], v[232:233], off offset:2048
	global_load_dwordx4 v[204:207], v[232:233], off offset:2064
	s_waitcnt vmcnt(8)
	v_pk_add_f32 v[174:175], v[174:175], v[208:209]
	v_pk_add_f32 v[176:177], v[176:177], v[210:211]
	v_pk_add_f32 v[178:179], v[178:179], v[212:213]
	v_pk_add_f32 v[180:181], v[180:181], v[214:215]
	v_pk_add_f32 v[182:183], v[182:183], v[216:217]
	v_pk_add_f32 v[184:185], v[184:185], v[218:219]
	v_pk_add_f32 v[186:187], v[186:187], v[220:221]
	v_pk_add_f32 v[188:189], v[188:189], v[222:223]
	s_mov_b64 s[0:1], 0x1c00000
	v_lshl_add_u64 v[232:233], v[36:37], 0, s[0:1]
	global_load_dwordx4 v[208:211], v[232:233], off
	global_load_dwordx4 v[212:215], v[232:233], off offset:16
	global_load_dwordx4 v[216:219], v[232:233], off offset:2048
	global_load_dwordx4 v[220:223], v[232:233], off offset:2064
	s_waitcnt vmcnt(8)
	v_pk_add_f32 v[174:175], v[174:175], v[224:225]
	v_pk_add_f32 v[176:177], v[176:177], v[226:227]
	v_pk_add_f32 v[178:179], v[178:179], v[228:229]
	v_pk_add_f32 v[180:181], v[180:181], v[230:231]
	v_pk_add_f32 v[182:183], v[182:183], v[238:239]
	v_pk_add_f32 v[184:185], v[184:185], v[240:241]
	v_pk_add_f32 v[186:187], v[186:187], v[242:243]
	v_pk_add_f32 v[188:189], v[188:189], v[244:245]
	s_mov_b64 s[0:1], 0x2000000
	v_lshl_add_u64 v[232:233], v[36:37], 0, s[0:1]
	global_load_dwordx4 v[224:227], v[232:233], off
	global_load_dwordx4 v[228:231], v[232:233], off offset:16
	global_load_dwordx4 v[238:241], v[232:233], off offset:2048
	global_load_dwordx4 v[242:245], v[232:233], off offset:2064
	s_waitcnt vmcnt(8)
	v_pk_add_f32 v[174:175], v[174:175], v[190:191]
	v_pk_add_f32 v[176:177], v[176:177], v[192:193]
	v_pk_add_f32 v[178:179], v[178:179], v[194:195]
	v_pk_add_f32 v[180:181], v[180:181], v[196:197]
	v_pk_add_f32 v[182:183], v[182:183], v[198:199]
	v_pk_add_f32 v[184:185], v[184:185], v[200:201]
	v_pk_add_f32 v[186:187], v[186:187], v[204:205]
	v_pk_add_f32 v[188:189], v[188:189], v[206:207]
	s_mov_b64 s[0:1], 0x2400000
	v_lshl_add_u64 v[232:233], v[36:37], 0, s[0:1]
	global_load_dwordx4 v[190:193], v[232:233], off
	global_load_dwordx4 v[194:197], v[232:233], off offset:16
	global_load_dwordx4 v[198:201], v[232:233], off offset:2048
	global_load_dwordx4 v[204:207], v[232:233], off offset:2064
	s_waitcnt vmcnt(8)
	v_pk_add_f32 v[174:175], v[174:175], v[208:209]
	v_pk_add_f32 v[176:177], v[176:177], v[210:211]
	v_pk_add_f32 v[178:179], v[178:179], v[212:213]
	v_pk_add_f32 v[180:181], v[180:181], v[214:215]
	v_pk_add_f32 v[182:183], v[182:183], v[216:217]
	v_pk_add_f32 v[184:185], v[184:185], v[218:219]
	v_pk_add_f32 v[186:187], v[186:187], v[220:221]
	v_pk_add_f32 v[188:189], v[188:189], v[222:223]
	s_mov_b64 s[0:1], 0x2800000
	v_lshl_add_u64 v[232:233], v[36:37], 0, s[0:1]
	global_load_dwordx4 v[208:211], v[232:233], off
	global_load_dwordx4 v[212:215], v[232:233], off offset:16
	global_load_dwordx4 v[216:219], v[232:233], off offset:2048
	global_load_dwordx4 v[220:223], v[232:233], off offset:2064
	s_waitcnt vmcnt(8)
	v_pk_add_f32 v[174:175], v[174:175], v[224:225]
	v_pk_add_f32 v[176:177], v[176:177], v[226:227]
	v_pk_add_f32 v[178:179], v[178:179], v[228:229]
	v_pk_add_f32 v[180:181], v[180:181], v[230:231]
	v_pk_add_f32 v[182:183], v[182:183], v[238:239]
	v_pk_add_f32 v[184:185], v[184:185], v[240:241]
	v_pk_add_f32 v[186:187], v[186:187], v[242:243]
	v_pk_add_f32 v[188:189], v[188:189], v[244:245]
	global_load_dwordx4 v[224:227], v[74:75], off
	global_load_dwordx4 v[228:231], v[74:75], off offset:16
	global_load_dwordx4 v[238:241], v[74:75], off offset:2048
	global_load_dwordx4 v[242:245], v[74:75], off offset:2064
	s_waitcnt vmcnt(8)
	v_pk_add_f32 v[174:175], v[174:175], v[190:191]
	v_pk_add_f32 v[176:177], v[176:177], v[192:193]
	v_pk_add_f32 v[178:179], v[178:179], v[194:195]
	v_pk_add_f32 v[180:181], v[180:181], v[196:197]
	v_pk_add_f32 v[182:183], v[182:183], v[198:199]
	v_pk_add_f32 v[184:185], v[184:185], v[200:201]
	v_pk_add_f32 v[186:187], v[186:187], v[204:205]
	v_pk_add_f32 v[188:189], v[188:189], v[206:207]
	s_mov_b64 s[0:1], 0x1000
	v_lshl_add_u64 v[232:233], v[36:37], 0, s[0:1]
	global_load_dwordx4 v[190:193], v[232:233], off
	global_load_dwordx4 v[194:197], v[232:233], off offset:16
	global_load_dwordx4 v[198:201], v[232:233], off offset:2048
	global_load_dwordx4 v[204:207], v[232:233], off offset:2064
	s_waitcnt vmcnt(8)
	v_pk_add_f32 v[174:175], v[174:175], v[208:209]
	v_pk_add_f32 v[176:177], v[176:177], v[210:211]
	v_pk_add_f32 v[178:179], v[178:179], v[212:213]
	v_pk_add_f32 v[180:181], v[180:181], v[214:215]
	v_pk_add_f32 v[182:183], v[182:183], v[216:217]
	v_pk_add_f32 v[184:185], v[184:185], v[218:219]
	v_pk_add_f32 v[186:187], v[186:187], v[220:221]
	v_pk_add_f32 v[188:189], v[188:189], v[222:223]
	s_mov_b64 s[0:1], 0x401000
	v_lshl_add_u64 v[232:233], v[36:37], 0, s[0:1]
	global_load_dwordx4 v[208:211], v[232:233], off
	global_load_dwordx4 v[212:215], v[232:233], off offset:16
	global_load_dwordx4 v[216:219], v[232:233], off offset:2048
	global_load_dwordx4 v[220:223], v[232:233], off offset:2064
	s_waitcnt vmcnt(8)
	v_pk_fma_f32 v[166:167], v[174:175], v[224:225], v[166:167]
	v_pk_fma_f32 v[162:163], v[176:177], v[226:227], v[162:163]
	v_pk_fma_f32 v[160:161], v[178:179], v[228:229], v[160:161]
	v_pk_fma_f32 v[164:165], v[180:181], v[230:231], v[164:165]
	v_pk_fma_f32 v[154:155], v[182:183], v[238:239], v[154:155]
	v_pk_fma_f32 v[156:157], v[184:185], v[240:241], v[156:157]
	v_pk_fma_f32 v[152:153], v[186:187], v[242:243], v[152:153]
	v_pk_fma_f32 v[158:159], v[188:189], v[244:245], v[158:159]
	s_mov_b64 s[0:1], 0x801000
	v_lshl_add_u64 v[232:233], v[36:37], 0, s[0:1]
	global_load_dwordx4 v[224:227], v[232:233], off
	global_load_dwordx4 v[228:231], v[232:233], off offset:16
	global_load_dwordx4 v[238:241], v[232:233], off offset:2048
	global_load_dwordx4 v[242:245], v[232:233], off offset:2064
	s_waitcnt vmcnt(8)
	v_mov_b64_e32 v[174:175], v[190:191]
	v_mov_b64_e32 v[176:177], v[192:193]
	v_mov_b64_e32 v[178:179], v[194:195]
	v_mov_b64_e32 v[180:181], v[196:197]
	v_mov_b64_e32 v[182:183], v[198:199]
	v_mov_b64_e32 v[184:185], v[200:201]
	v_mov_b64_e32 v[186:187], v[204:205]
	v_mov_b64_e32 v[188:189], v[206:207]
	s_mov_b64 s[0:1], 0xc01000
	v_lshl_add_u64 v[232:233], v[36:37], 0, s[0:1]
	global_load_dwordx4 v[190:193], v[232:233], off
	global_load_dwordx4 v[194:197], v[232:233], off offset:16
	global_load_dwordx4 v[198:201], v[232:233], off offset:2048
	global_load_dwordx4 v[204:207], v[232:233], off offset:2064
	s_waitcnt vmcnt(8)
	v_pk_add_f32 v[174:175], v[174:175], v[208:209]
	v_pk_add_f32 v[176:177], v[176:177], v[210:211]
	v_pk_add_f32 v[178:179], v[178:179], v[212:213]
	v_pk_add_f32 v[180:181], v[180:181], v[214:215]
	v_pk_add_f32 v[182:183], v[182:183], v[216:217]
	v_pk_add_f32 v[184:185], v[184:185], v[218:219]
	v_pk_add_f32 v[186:187], v[186:187], v[220:221]
	v_pk_add_f32 v[188:189], v[188:189], v[222:223]
	s_mov_b64 s[0:1], 0x1001000
	v_lshl_add_u64 v[232:233], v[36:37], 0, s[0:1]
	global_load_dwordx4 v[208:211], v[232:233], off
	global_load_dwordx4 v[212:215], v[232:233], off offset:16
	global_load_dwordx4 v[216:219], v[232:233], off offset:2048
	global_load_dwordx4 v[220:223], v[232:233], off offset:2064
	s_waitcnt vmcnt(8)
	v_pk_add_f32 v[174:175], v[174:175], v[224:225]
	v_pk_add_f32 v[176:177], v[176:177], v[226:227]
	v_pk_add_f32 v[178:179], v[178:179], v[228:229]
	v_pk_add_f32 v[180:181], v[180:181], v[230:231]
	v_pk_add_f32 v[182:183], v[182:183], v[238:239]
	v_pk_add_f32 v[184:185], v[184:185], v[240:241]
	v_pk_add_f32 v[186:187], v[186:187], v[242:243]
	v_pk_add_f32 v[188:189], v[188:189], v[244:245]
	s_mov_b64 s[0:1], 0x1401000
	v_lshl_add_u64 v[232:233], v[36:37], 0, s[0:1]
	global_load_dwordx4 v[224:227], v[232:233], off
	global_load_dwordx4 v[228:231], v[232:233], off offset:16
	global_load_dwordx4 v[238:241], v[232:233], off offset:2048
	global_load_dwordx4 v[242:245], v[232:233], off offset:2064
	s_waitcnt vmcnt(8)
	v_pk_add_f32 v[174:175], v[174:175], v[190:191]
	v_pk_add_f32 v[176:177], v[176:177], v[192:193]
	v_pk_add_f32 v[178:179], v[178:179], v[194:195]
	v_pk_add_f32 v[180:181], v[180:181], v[196:197]
	v_pk_add_f32 v[182:183], v[182:183], v[198:199]
	v_pk_add_f32 v[184:185], v[184:185], v[200:201]
	v_pk_add_f32 v[186:187], v[186:187], v[204:205]
	v_pk_add_f32 v[188:189], v[188:189], v[206:207]
	s_mov_b64 s[0:1], 0x1801000
	v_lshl_add_u64 v[232:233], v[36:37], 0, s[0:1]
	global_load_dwordx4 v[190:193], v[232:233], off
	global_load_dwordx4 v[194:197], v[232:233], off offset:16
	global_load_dwordx4 v[198:201], v[232:233], off offset:2048
	global_load_dwordx4 v[204:207], v[232:233], off offset:2064
	s_waitcnt vmcnt(8)
	v_pk_add_f32 v[174:175], v[174:175], v[208:209]
	v_pk_add_f32 v[176:177], v[176:177], v[210:211]
	v_pk_add_f32 v[178:179], v[178:179], v[212:213]
	v_pk_add_f32 v[180:181], v[180:181], v[214:215]
	v_pk_add_f32 v[182:183], v[182:183], v[216:217]
	v_pk_add_f32 v[184:185], v[184:185], v[218:219]
	v_pk_add_f32 v[186:187], v[186:187], v[220:221]
	v_pk_add_f32 v[188:189], v[188:189], v[222:223]
	s_mov_b64 s[0:1], 0x1c01000
	v_lshl_add_u64 v[232:233], v[36:37], 0, s[0:1]
	global_load_dwordx4 v[208:211], v[232:233], off
	global_load_dwordx4 v[212:215], v[232:233], off offset:16
	global_load_dwordx4 v[216:219], v[232:233], off offset:2048
	global_load_dwordx4 v[220:223], v[232:233], off offset:2064
	s_waitcnt vmcnt(8)
	v_pk_add_f32 v[174:175], v[174:175], v[224:225]
	v_pk_add_f32 v[176:177], v[176:177], v[226:227]
	v_pk_add_f32 v[178:179], v[178:179], v[228:229]
	v_pk_add_f32 v[180:181], v[180:181], v[230:231]
	v_pk_add_f32 v[182:183], v[182:183], v[238:239]
	v_pk_add_f32 v[184:185], v[184:185], v[240:241]
	v_pk_add_f32 v[186:187], v[186:187], v[242:243]
	v_pk_add_f32 v[188:189], v[188:189], v[244:245]
	s_mov_b64 s[0:1], 0x2001000
	v_lshl_add_u64 v[232:233], v[36:37], 0, s[0:1]
	global_load_dwordx4 v[224:227], v[232:233], off
	global_load_dwordx4 v[228:231], v[232:233], off offset:16
	global_load_dwordx4 v[238:241], v[232:233], off offset:2048
	global_load_dwordx4 v[242:245], v[232:233], off offset:2064
	s_waitcnt vmcnt(8)
	v_pk_add_f32 v[174:175], v[174:175], v[190:191]
	v_pk_add_f32 v[176:177], v[176:177], v[192:193]
	v_pk_add_f32 v[178:179], v[178:179], v[194:195]
	v_pk_add_f32 v[180:181], v[180:181], v[196:197]
	v_pk_add_f32 v[182:183], v[182:183], v[198:199]
	v_pk_add_f32 v[184:185], v[184:185], v[200:201]
	v_pk_add_f32 v[186:187], v[186:187], v[204:205]
	v_pk_add_f32 v[188:189], v[188:189], v[206:207]
	s_mov_b64 s[0:1], 0x2401000
	v_lshl_add_u64 v[232:233], v[36:37], 0, s[0:1]
	global_load_dwordx4 v[190:193], v[232:233], off
	global_load_dwordx4 v[194:197], v[232:233], off offset:16
	global_load_dwordx4 v[198:201], v[232:233], off offset:2048
	global_load_dwordx4 v[204:207], v[232:233], off offset:2064
	s_waitcnt vmcnt(8)
	v_pk_add_f32 v[174:175], v[174:175], v[208:209]
	v_pk_add_f32 v[176:177], v[176:177], v[210:211]
	v_pk_add_f32 v[178:179], v[178:179], v[212:213]
	v_pk_add_f32 v[180:181], v[180:181], v[214:215]
	v_pk_add_f32 v[182:183], v[182:183], v[216:217]
	v_pk_add_f32 v[184:185], v[184:185], v[218:219]
	v_pk_add_f32 v[186:187], v[186:187], v[220:221]
	v_pk_add_f32 v[188:189], v[188:189], v[222:223]
	s_mov_b64 s[0:1], 0x2801000
	v_lshl_add_u64 v[232:233], v[36:37], 0, s[0:1]
	global_load_dwordx4 v[208:211], v[232:233], off
	global_load_dwordx4 v[212:215], v[232:233], off offset:16
	global_load_dwordx4 v[216:219], v[232:233], off offset:2048
	global_load_dwordx4 v[220:223], v[232:233], off offset:2064
	s_waitcnt vmcnt(8)
	v_pk_add_f32 v[174:175], v[174:175], v[224:225]
	v_pk_add_f32 v[176:177], v[176:177], v[226:227]
	v_pk_add_f32 v[178:179], v[178:179], v[228:229]
	v_pk_add_f32 v[180:181], v[180:181], v[230:231]
	v_pk_add_f32 v[182:183], v[182:183], v[238:239]
	v_pk_add_f32 v[184:185], v[184:185], v[240:241]
	v_pk_add_f32 v[186:187], v[186:187], v[242:243]
	v_pk_add_f32 v[188:189], v[188:189], v[244:245]
	global_load_dwordx4 v[224:227], v[76:77], off
	global_load_dwordx4 v[228:231], v[76:77], off offset:16
	global_load_dwordx4 v[238:241], v[78:79], off
	global_load_dwordx4 v[242:245], v[78:79], off offset:16
	s_waitcnt vmcnt(8)
	v_pk_add_f32 v[174:175], v[174:175], v[190:191]
	v_pk_add_f32 v[176:177], v[176:177], v[192:193]
	v_pk_add_f32 v[178:179], v[178:179], v[194:195]
	v_pk_add_f32 v[180:181], v[180:181], v[196:197]
	v_pk_add_f32 v[182:183], v[182:183], v[198:199]
	v_pk_add_f32 v[184:185], v[184:185], v[200:201]
	v_pk_add_f32 v[186:187], v[186:187], v[204:205]
	v_pk_add_f32 v[188:189], v[188:189], v[206:207]
	s_waitcnt vmcnt(4)
	v_pk_add_f32 v[174:175], v[174:175], v[208:209]
	v_pk_add_f32 v[176:177], v[176:177], v[210:211]
	v_pk_add_f32 v[178:179], v[178:179], v[212:213]
	v_pk_add_f32 v[180:181], v[180:181], v[214:215]
	v_pk_add_f32 v[182:183], v[182:183], v[216:217]
	v_pk_add_f32 v[184:185], v[184:185], v[218:219]
	v_pk_add_f32 v[186:187], v[186:187], v[220:221]
	v_pk_add_f32 v[188:189], v[188:189], v[222:223]
	s_waitcnt vmcnt(0)
	v_pk_fma_f32 v[44:45], v[174:175], v[224:225], v[44:45]
	v_pk_fma_f32 v[46:47], v[176:177], v[226:227], v[46:47]
	v_pk_fma_f32 v[42:43], v[178:179], v[228:229], v[42:43]
	v_pk_fma_f32 v[48:49], v[180:181], v[230:231], v[48:49]
	v_pk_fma_f32 v[38:39], v[182:183], v[238:239], v[38:39]
	v_pk_fma_f32 v[40:41], v[184:185], v[240:241], v[40:41]
	v_pk_fma_f32 v[32:33], v[186:187], v[242:243], v[32:33]
	v_pk_fma_f32 v[34:35], v[188:189], v[244:245], v[34:35]

.LBB0_1812:
	s_add_i32 s0, s75, s4
	s_cmpk_lt_i32 s0, 0x4200
	s_cselect_b32 s0, s0, s4
	s_ashr_i32 s1, s0, 31
	s_lshl_b64 s[0:1], s[0:1], 12
	v_lshl_add_u64 v[32:33], v[80:81], 0, s[0:1]
	global_load_dwordx4 v[46:49], v[32:33], off
	global_load_dwordx4 v[42:45], v[32:33], off offset:1024
	global_load_dwordx4 v[38:41], v[32:33], off offset:2048
	global_load_dwordx4 v[34:37], v[32:33], off offset:3072
	s_waitcnt vmcnt(4)
	s_andn2_b64 vcc, exec, s[8:9]
	s_cbranch_vccnz .LBB0_1802
	v_cvt_f32_f16_sdwa v167, v62 dst_sel:DWORD dst_unused:UNUSED_PAD src0_sel:WORD_1
	v_cvt_f32_f16_e32 v166, v62
	v_cvt_f32_f16_sdwa v163, v63 dst_sel:DWORD dst_unused:UNUSED_PAD src0_sel:WORD_1
	v_cvt_f32_f16_e32 v162, v63
	v_cvt_f32_f16_sdwa v161, v64 dst_sel:DWORD dst_unused:UNUSED_PAD src0_sel:WORD_1
	v_cvt_f32_f16_e32 v160, v64
	v_cvt_f32_f16_sdwa v165, v65 dst_sel:DWORD dst_unused:UNUSED_PAD src0_sel:WORD_1
	v_cvt_f32_f16_e32 v164, v65
	v_cvt_f32_f16_sdwa v155, v58 dst_sel:DWORD dst_unused:UNUSED_PAD src0_sel:WORD_1
	v_cvt_f32_f16_e32 v154, v58
	v_cvt_f32_f16_sdwa v157, v59 dst_sel:DWORD dst_unused:UNUSED_PAD src0_sel:WORD_1
	v_cvt_f32_f16_e32 v156, v59
	v_cvt_f32_f16_sdwa v153, v60 dst_sel:DWORD dst_unused:UNUSED_PAD src0_sel:WORD_1
	v_cvt_f32_f16_e32 v152, v60
	v_cvt_f32_f16_sdwa v159, v61 dst_sel:DWORD dst_unused:UNUSED_PAD src0_sel:WORD_1
	v_cvt_f32_f16_e32 v158, v61
	v_cvt_f32_f16_sdwa v61, v54 dst_sel:DWORD dst_unused:UNUSED_PAD src0_sel:WORD_1
	v_cvt_f32_f16_e32 v60, v54
	v_cvt_f32_f16_sdwa v63, v55 dst_sel:DWORD dst_unused:UNUSED_PAD src0_sel:WORD_1
	v_cvt_f32_f16_e32 v62, v55
	v_cvt_f32_f16_sdwa v59, v56 dst_sel:DWORD dst_unused:UNUSED_PAD src0_sel:WORD_1
	v_cvt_f32_f16_e32 v58, v56
	v_cvt_f32_f16_sdwa v65, v57 dst_sel:DWORD dst_unused:UNUSED_PAD src0_sel:WORD_1
	v_cvt_f32_f16_e32 v64, v57
	v_cvt_f32_f16_sdwa v55, v50 dst_sel:DWORD dst_unused:UNUSED_PAD src0_sel:WORD_1
	v_cvt_f32_f16_e32 v54, v50
	v_cvt_f32_f16_sdwa v57, v51 dst_sel:DWORD dst_unused:UNUSED_PAD src0_sel:WORD_1
	v_cvt_f32_f16_e32 v56, v51
	v_cvt_f32_f16_sdwa v33, v52 dst_sel:DWORD dst_unused:UNUSED_PAD src0_sel:WORD_1
	v_cvt_f32_f16_e32 v32, v52
	v_cvt_f32_f16_sdwa v51, v53 dst_sel:DWORD dst_unused:UNUSED_PAD src0_sel:WORD_1
	v_cvt_f32_f16_e32 v50, v53
	s_cmpk_gt_i32 s14, 0x3fff
	s_cselect_b64 s[2:3], -1, 0
	s_cmpk_lt_i32 s14, 0x4000
	s_cbranch_scc1 .LBB0_1815
	s_add_i32 s86, s14, 0xffffc000
	s_lshl_b64 s[0:1], s[86:87], 13
	v_lshl_add_u64 v[52:53], v[82:83], 0, s[0:1]
	global_load_dwordx4 v[190:193], v[52:53], off
	global_load_dwordx4 v[194:197], v[52:53], off offset:16
	global_load_dwordx4 v[198:201], v[52:53], off offset:2048
	global_load_dwordx4 v[204:207], v[52:53], off offset:2064
	s_mov_b64 s[0:1], 0x400000
	v_lshl_add_u64 v[232:233], v[52:53], 0, s[0:1]
	global_load_dwordx4 v[208:211], v[232:233], off
	global_load_dwordx4 v[212:215], v[232:233], off offset:16
	global_load_dwordx4 v[216:219], v[232:233], off offset:2048
	global_load_dwordx4 v[220:223], v[232:233], off offset:2064
	s_mov_b64 s[0:1], 0x800000
	v_lshl_add_u64 v[232:233], v[52:53], 0, s[0:1]
	global_load_dwordx4 v[224:227], v[232:233], off
	global_load_dwordx4 v[228:231], v[232:233], off offset:16
	global_load_dwordx4 v[238:241], v[232:233], off offset:2048
	global_load_dwordx4 v[242:245], v[232:233], off offset:2064
	s_waitcnt vmcnt(8)
	v_mov_b64_e32 v[174:175], v[190:191]
	v_mov_b64_e32 v[176:177], v[192:193]
	v_mov_b64_e32 v[178:179], v[194:195]
	v_mov_b64_e32 v[180:181], v[196:197]
	v_mov_b64_e32 v[182:183], v[198:199]
	v_mov_b64_e32 v[184:185], v[200:201]
	v_mov_b64_e32 v[186:187], v[204:205]
	v_mov_b64_e32 v[188:189], v[206:207]
	s_mov_b64 s[0:1], 0xc00000
	v_lshl_add_u64 v[232:233], v[52:53], 0, s[0:1]
	global_load_dwordx4 v[190:193], v[232:233], off
	global_load_dwordx4 v[194:197], v[232:233], off offset:16
	global_load_dwordx4 v[198:201], v[232:233], off offset:2048
	global_load_dwordx4 v[204:207], v[232:233], off offset:2064
	s_waitcnt vmcnt(8)
	v_pk_add_f32 v[174:175], v[174:175], v[208:209]
	v_pk_add_f32 v[176:177], v[176:177], v[210:211]
	v_pk_add_f32 v[178:179], v[178:179], v[212:213]
	v_pk_add_f32 v[180:181], v[180:181], v[214:215]
	v_pk_add_f32 v[182:183], v[182:183], v[216:217]
	v_pk_add_f32 v[184:185], v[184:185], v[218:219]
	v_pk_add_f32 v[186:187], v[186:187], v[220:221]
	v_pk_add_f32 v[188:189], v[188:189], v[222:223]
	s_mov_b64 s[0:1], 0x1000000
	v_lshl_add_u64 v[232:233], v[52:53], 0, s[0:1]
	global_load_dwordx4 v[208:211], v[232:233], off
	global_load_dwordx4 v[212:215], v[232:233], off offset:16
	global_load_dwordx4 v[216:219], v[232:233], off offset:2048
	global_load_dwordx4 v[220:223], v[232:233], off offset:2064
	s_waitcnt vmcnt(8)
	v_pk_add_f32 v[174:175], v[174:175], v[224:225]
	v_pk_add_f32 v[176:177], v[176:177], v[226:227]
	v_pk_add_f32 v[178:179], v[178:179], v[228:229]
	v_pk_add_f32 v[180:181], v[180:181], v[230:231]
	v_pk_add_f32 v[182:183], v[182:183], v[238:239]
	v_pk_add_f32 v[184:185], v[184:185], v[240:241]
	v_pk_add_f32 v[186:187], v[186:187], v[242:243]
	v_pk_add_f32 v[188:189], v[188:189], v[244:245]
	s_mov_b64 s[0:1], 0x1400000
	v_lshl_add_u64 v[232:233], v[52:53], 0, s[0:1]
	global_load_dwordx4 v[224:227], v[232:233], off
	global_load_dwordx4 v[228:231], v[232:233], off offset:16
	global_load_dwordx4 v[238:241], v[232:233], off offset:2048
	global_load_dwordx4 v[242:245], v[232:233], off offset:2064
	s_waitcnt vmcnt(8)
	v_pk_add_f32 v[174:175], v[174:175], v[190:191]
	v_pk_add_f32 v[176:177], v[176:177], v[192:193]
	v_pk_add_f32 v[178:179], v[178:179], v[194:195]
	v_pk_add_f32 v[180:181], v[180:181], v[196:197]
	v_pk_add_f32 v[182:183], v[182:183], v[198:199]
	v_pk_add_f32 v[184:185], v[184:185], v[200:201]
	v_pk_add_f32 v[186:187], v[186:187], v[204:205]
	v_pk_add_f32 v[188:189], v[188:189], v[206:207]
	s_mov_b64 s[0:1], 0x1800000
	v_lshl_add_u64 v[232:233], v[52:53], 0, s[0:1]
	global_load_dwordx4 v[190:193], v[232:233], off
	global_load_dwordx4 v[194:197], v[232:233], off offset:16
	global_load_dwordx4 v[198:201], v[232:233], off offset:2048
	global_load_dwordx4 v[204:207], v[232:233], off offset:2064
	s_waitcnt vmcnt(8)
	v_pk_add_f32 v[174:175], v[174:175], v[208:209]
	v_pk_add_f32 v[176:177], v[176:177], v[210:211]
	v_pk_add_f32 v[178:179], v[178:179], v[212:213]
	v_pk_add_f32 v[180:181], v[180:181], v[214:215]
	v_pk_add_f32 v[182:183], v[182:183], v[216:217]
	v_pk_add_f32 v[184:185], v[184:185], v[218:219]
	v_pk_add_f32 v[186:187], v[186:187], v[220:221]
	v_pk_add_f32 v[188:189], v[188:189], v[222:223]
	s_mov_b64 s[0:1], 0x1c00000
	v_lshl_add_u64 v[232:233], v[52:53], 0, s[0:1]
	global_load_dwordx4 v[208:211], v[232:233], off
	global_load_dwordx4 v[212:215], v[232:233], off offset:16
	global_load_dwordx4 v[216:219], v[232:233], off offset:2048
	global_load_dwordx4 v[220:223], v[232:233], off offset:2064
	s_waitcnt vmcnt(8)
	v_pk_add_f32 v[174:175], v[174:175], v[224:225]
	v_pk_add_f32 v[176:177], v[176:177], v[226:227]
	v_pk_add_f32 v[178:179], v[178:179], v[228:229]
	v_pk_add_f32 v[180:181], v[180:181], v[230:231]
	v_pk_add_f32 v[182:183], v[182:183], v[238:239]
	v_pk_add_f32 v[184:185], v[184:185], v[240:241]
	v_pk_add_f32 v[186:187], v[186:187], v[242:243]
	v_pk_add_f32 v[188:189], v[188:189], v[244:245]
	s_mov_b64 s[0:1], 0x2000000
	v_lshl_add_u64 v[232:233], v[52:53], 0, s[0:1]
	global_load_dwordx4 v[224:227], v[232:233], off
	global_load_dwordx4 v[228:231], v[232:233], off offset:16
	global_load_dwordx4 v[238:241], v[232:233], off offset:2048
	global_load_dwordx4 v[242:245], v[232:233], off offset:2064
	s_waitcnt vmcnt(8)
	v_pk_add_f32 v[174:175], v[174:175], v[190:191]
	v_pk_add_f32 v[176:177], v[176:177], v[192:193]
	v_pk_add_f32 v[178:179], v[178:179], v[194:195]
	v_pk_add_f32 v[180:181], v[180:181], v[196:197]
	v_pk_add_f32 v[182:183], v[182:183], v[198:199]
	v_pk_add_f32 v[184:185], v[184:185], v[200:201]
	v_pk_add_f32 v[186:187], v[186:187], v[204:205]
	v_pk_add_f32 v[188:189], v[188:189], v[206:207]
	s_mov_b64 s[0:1], 0x2400000
	v_lshl_add_u64 v[232:233], v[52:53], 0, s[0:1]
	global_load_dwordx4 v[190:193], v[232:233], off
	global_load_dwordx4 v[194:197], v[232:233], off offset:16
	global_load_dwordx4 v[198:201], v[232:233], off offset:2048
	global_load_dwordx4 v[204:207], v[232:233], off offset:2064
	s_waitcnt vmcnt(8)
	v_pk_add_f32 v[174:175], v[174:175], v[208:209]
	v_pk_add_f32 v[176:177], v[176:177], v[210:211]
	v_pk_add_f32 v[178:179], v[178:179], v[212:213]
	v_pk_add_f32 v[180:181], v[180:181], v[214:215]
	v_pk_add_f32 v[182:183], v[182:183], v[216:217]
	v_pk_add_f32 v[184:185], v[184:185], v[218:219]
	v_pk_add_f32 v[186:187], v[186:187], v[220:221]
	v_pk_add_f32 v[188:189], v[188:189], v[222:223]
	s_mov_b64 s[0:1], 0x2800000
	v_lshl_add_u64 v[232:233], v[52:53], 0, s[0:1]
	global_load_dwordx4 v[208:211], v[232:233], off
	global_load_dwordx4 v[212:215], v[232:233], off offset:16
	global_load_dwordx4 v[216:219], v[232:233], off offset:2048
	global_load_dwordx4 v[220:223], v[232:233], off offset:2064
	s_waitcnt vmcnt(8)
	v_pk_add_f32 v[174:175], v[174:175], v[224:225]
	v_pk_add_f32 v[176:177], v[176:177], v[226:227]
	v_pk_add_f32 v[178:179], v[178:179], v[228:229]
	v_pk_add_f32 v[180:181], v[180:181], v[230:231]
	v_pk_add_f32 v[182:183], v[182:183], v[238:239]
	v_pk_add_f32 v[184:185], v[184:185], v[240:241]
	v_pk_add_f32 v[186:187], v[186:187], v[242:243]
	v_pk_add_f32 v[188:189], v[188:189], v[244:245]
	global_load_dwordx4 v[224:227], v[74:75], off
	global_load_dwordx4 v[228:231], v[74:75], off offset:16
	global_load_dwordx4 v[238:241], v[74:75], off offset:2048
	global_load_dwordx4 v[242:245], v[74:75], off offset:2064
	s_waitcnt vmcnt(8)
	v_pk_add_f32 v[174:175], v[174:175], v[190:191]
	v_pk_add_f32 v[176:177], v[176:177], v[192:193]
	v_pk_add_f32 v[178:179], v[178:179], v[194:195]
	v_pk_add_f32 v[180:181], v[180:181], v[196:197]
	v_pk_add_f32 v[182:183], v[182:183], v[198:199]
	v_pk_add_f32 v[184:185], v[184:185], v[200:201]
	v_pk_add_f32 v[186:187], v[186:187], v[204:205]
	v_pk_add_f32 v[188:189], v[188:189], v[206:207]
	s_mov_b64 s[0:1], 0x1000
	v_lshl_add_u64 v[232:233], v[52:53], 0, s[0:1]
	global_load_dwordx4 v[190:193], v[232:233], off
	global_load_dwordx4 v[194:197], v[232:233], off offset:16
	global_load_dwordx4 v[198:201], v[232:233], off offset:2048
	global_load_dwordx4 v[204:207], v[232:233], off offset:2064
	s_waitcnt vmcnt(8)
	v_pk_add_f32 v[174:175], v[174:175], v[208:209]
	v_pk_add_f32 v[176:177], v[176:177], v[210:211]
	v_pk_add_f32 v[178:179], v[178:179], v[212:213]
	v_pk_add_f32 v[180:181], v[180:181], v[214:215]
	v_pk_add_f32 v[182:183], v[182:183], v[216:217]
	v_pk_add_f32 v[184:185], v[184:185], v[218:219]
	v_pk_add_f32 v[186:187], v[186:187], v[220:221]
	v_pk_add_f32 v[188:189], v[188:189], v[222:223]
	s_mov_b64 s[0:1], 0x401000
	v_lshl_add_u64 v[232:233], v[52:53], 0, s[0:1]
	global_load_dwordx4 v[208:211], v[232:233], off
	global_load_dwordx4 v[212:215], v[232:233], off offset:16
	global_load_dwordx4 v[216:219], v[232:233], off offset:2048
	global_load_dwordx4 v[220:223], v[232:233], off offset:2064
	s_waitcnt vmcnt(8)
	v_pk_fma_f32 v[166:167], v[174:175], v[224:225], v[166:167]
	v_pk_fma_f32 v[162:163], v[176:177], v[226:227], v[162:163]
	v_pk_fma_f32 v[160:161], v[178:179], v[228:229], v[160:161]
	v_pk_fma_f32 v[164:165], v[180:181], v[230:231], v[164:165]
	v_pk_fma_f32 v[154:155], v[182:183], v[238:239], v[154:155]
	v_pk_fma_f32 v[156:157], v[184:185], v[240:241], v[156:157]
	v_pk_fma_f32 v[152:153], v[186:187], v[242:243], v[152:153]
	v_pk_fma_f32 v[158:159], v[188:189], v[244:245], v[158:159]
	s_mov_b64 s[0:1], 0x801000
	v_lshl_add_u64 v[232:233], v[52:53], 0, s[0:1]
	global_load_dwordx4 v[224:227], v[232:233], off
	global_load_dwordx4 v[228:231], v[232:233], off offset:16
	global_load_dwordx4 v[238:241], v[232:233], off offset:2048
	global_load_dwordx4 v[242:245], v[232:233], off offset:2064
	s_waitcnt vmcnt(8)
	v_mov_b64_e32 v[174:175], v[190:191]
	v_mov_b64_e32 v[176:177], v[192:193]
	v_mov_b64_e32 v[178:179], v[194:195]
	v_mov_b64_e32 v[180:181], v[196:197]
	v_mov_b64_e32 v[182:183], v[198:199]
	v_mov_b64_e32 v[184:185], v[200:201]
	v_mov_b64_e32 v[186:187], v[204:205]
	v_mov_b64_e32 v[188:189], v[206:207]
	s_mov_b64 s[0:1], 0xc01000
	v_lshl_add_u64 v[232:233], v[52:53], 0, s[0:1]
	global_load_dwordx4 v[190:193], v[232:233], off
	global_load_dwordx4 v[194:197], v[232:233], off offset:16
	global_load_dwordx4 v[198:201], v[232:233], off offset:2048
	global_load_dwordx4 v[204:207], v[232:233], off offset:2064
	s_waitcnt vmcnt(8)
	v_pk_add_f32 v[174:175], v[174:175], v[208:209]
	v_pk_add_f32 v[176:177], v[176:177], v[210:211]
	v_pk_add_f32 v[178:179], v[178:179], v[212:213]
	v_pk_add_f32 v[180:181], v[180:181], v[214:215]
	v_pk_add_f32 v[182:183], v[182:183], v[216:217]
	v_pk_add_f32 v[184:185], v[184:185], v[218:219]
	v_pk_add_f32 v[186:187], v[186:187], v[220:221]
	v_pk_add_f32 v[188:189], v[188:189], v[222:223]
	s_mov_b64 s[0:1], 0x1001000
	v_lshl_add_u64 v[232:233], v[52:53], 0, s[0:1]
	global_load_dwordx4 v[208:211], v[232:233], off
	global_load_dwordx4 v[212:215], v[232:233], off offset:16
	global_load_dwordx4 v[216:219], v[232:233], off offset:2048
	global_load_dwordx4 v[220:223], v[232:233], off offset:2064
	s_waitcnt vmcnt(8)
	v_pk_add_f32 v[174:175], v[174:175], v[224:225]
	v_pk_add_f32 v[176:177], v[176:177], v[226:227]
	v_pk_add_f32 v[178:179], v[178:179], v[228:229]
	v_pk_add_f32 v[180:181], v[180:181], v[230:231]
	v_pk_add_f32 v[182:183], v[182:183], v[238:239]
	v_pk_add_f32 v[184:185], v[184:185], v[240:241]
	v_pk_add_f32 v[186:187], v[186:187], v[242:243]
	v_pk_add_f32 v[188:189], v[188:189], v[244:245]
	s_mov_b64 s[0:1], 0x1401000
	v_lshl_add_u64 v[232:233], v[52:53], 0, s[0:1]
	global_load_dwordx4 v[224:227], v[232:233], off
	global_load_dwordx4 v[228:231], v[232:233], off offset:16
	global_load_dwordx4 v[238:241], v[232:233], off offset:2048
	global_load_dwordx4 v[242:245], v[232:233], off offset:2064
	s_waitcnt vmcnt(8)
	v_pk_add_f32 v[174:175], v[174:175], v[190:191]
	v_pk_add_f32 v[176:177], v[176:177], v[192:193]
	v_pk_add_f32 v[178:179], v[178:179], v[194:195]
	v_pk_add_f32 v[180:181], v[180:181], v[196:197]
	v_pk_add_f32 v[182:183], v[182:183], v[198:199]
	v_pk_add_f32 v[184:185], v[184:185], v[200:201]
	v_pk_add_f32 v[186:187], v[186:187], v[204:205]
	v_pk_add_f32 v[188:189], v[188:189], v[206:207]
	s_mov_b64 s[0:1], 0x1801000
	v_lshl_add_u64 v[232:233], v[52:53], 0, s[0:1]
	global_load_dwordx4 v[190:193], v[232:233], off
	global_load_dwordx4 v[194:197], v[232:233], off offset:16
	global_load_dwordx4 v[198:201], v[232:233], off offset:2048
	global_load_dwordx4 v[204:207], v[232:233], off offset:2064
	s_waitcnt vmcnt(8)
	v_pk_add_f32 v[174:175], v[174:175], v[208:209]
	v_pk_add_f32 v[176:177], v[176:177], v[210:211]
	v_pk_add_f32 v[178:179], v[178:179], v[212:213]
	v_pk_add_f32 v[180:181], v[180:181], v[214:215]
	v_pk_add_f32 v[182:183], v[182:183], v[216:217]
	v_pk_add_f32 v[184:185], v[184:185], v[218:219]
	v_pk_add_f32 v[186:187], v[186:187], v[220:221]
	v_pk_add_f32 v[188:189], v[188:189], v[222:223]
	s_mov_b64 s[0:1], 0x1c01000
	v_lshl_add_u64 v[232:233], v[52:53], 0, s[0:1]
	global_load_dwordx4 v[208:211], v[232:233], off
	global_load_dwordx4 v[212:215], v[232:233], off offset:16
	global_load_dwordx4 v[216:219], v[232:233], off offset:2048
	global_load_dwordx4 v[220:223], v[232:233], off offset:2064
	s_waitcnt vmcnt(8)
	v_pk_add_f32 v[174:175], v[174:175], v[224:225]
	v_pk_add_f32 v[176:177], v[176:177], v[226:227]
	v_pk_add_f32 v[178:179], v[178:179], v[228:229]
	v_pk_add_f32 v[180:181], v[180:181], v[230:231]
	v_pk_add_f32 v[182:183], v[182:183], v[238:239]
	v_pk_add_f32 v[184:185], v[184:185], v[240:241]
	v_pk_add_f32 v[186:187], v[186:187], v[242:243]
	v_pk_add_f32 v[188:189], v[188:189], v[244:245]
	s_mov_b64 s[0:1], 0x2001000
	v_lshl_add_u64 v[232:233], v[52:53], 0, s[0:1]
	global_load_dwordx4 v[224:227], v[232:233], off
	global_load_dwordx4 v[228:231], v[232:233], off offset:16
	global_load_dwordx4 v[238:241], v[232:233], off offset:2048
	global_load_dwordx4 v[242:245], v[232:233], off offset:2064
	s_waitcnt vmcnt(8)
	v_pk_add_f32 v[174:175], v[174:175], v[190:191]
	v_pk_add_f32 v[176:177], v[176:177], v[192:193]
	v_pk_add_f32 v[178:179], v[178:179], v[194:195]
	v_pk_add_f32 v[180:181], v[180:181], v[196:197]
	v_pk_add_f32 v[182:183], v[182:183], v[198:199]
	v_pk_add_f32 v[184:185], v[184:185], v[200:201]
	v_pk_add_f32 v[186:187], v[186:187], v[204:205]
	v_pk_add_f32 v[188:189], v[188:189], v[206:207]
	s_mov_b64 s[0:1], 0x2401000
	v_lshl_add_u64 v[232:233], v[52:53], 0, s[0:1]
	global_load_dwordx4 v[190:193], v[232:233], off
	global_load_dwordx4 v[194:197], v[232:233], off offset:16
	global_load_dwordx4 v[198:201], v[232:233], off offset:2048
	global_load_dwordx4 v[204:207], v[232:233], off offset:2064
	s_waitcnt vmcnt(8)
	v_pk_add_f32 v[174:175], v[174:175], v[208:209]
	v_pk_add_f32 v[176:177], v[176:177], v[210:211]
	v_pk_add_f32 v[178:179], v[178:179], v[212:213]
	v_pk_add_f32 v[180:181], v[180:181], v[214:215]
	v_pk_add_f32 v[182:183], v[182:183], v[216:217]
	v_pk_add_f32 v[184:185], v[184:185], v[218:219]
	v_pk_add_f32 v[186:187], v[186:187], v[220:221]
	v_pk_add_f32 v[188:189], v[188:189], v[222:223]
	s_mov_b64 s[0:1], 0x2801000
	v_lshl_add_u64 v[232:233], v[52:53], 0, s[0:1]
	global_load_dwordx4 v[208:211], v[232:233], off
	global_load_dwordx4 v[212:215], v[232:233], off offset:16
	global_load_dwordx4 v[216:219], v[232:233], off offset:2048
	global_load_dwordx4 v[220:223], v[232:233], off offset:2064
	s_waitcnt vmcnt(8)
	v_pk_add_f32 v[174:175], v[174:175], v[224:225]
	v_pk_add_f32 v[176:177], v[176:177], v[226:227]
	v_pk_add_f32 v[178:179], v[178:179], v[228:229]
	v_pk_add_f32 v[180:181], v[180:181], v[230:231]
	v_pk_add_f32 v[182:183], v[182:183], v[238:239]
	v_pk_add_f32 v[184:185], v[184:185], v[240:241]
	v_pk_add_f32 v[186:187], v[186:187], v[242:243]
	v_pk_add_f32 v[188:189], v[188:189], v[244:245]
	global_load_dwordx4 v[224:227], v[76:77], off
	global_load_dwordx4 v[228:231], v[76:77], off offset:16
	global_load_dwordx4 v[238:241], v[78:79], off
	global_load_dwordx4 v[242:245], v[78:79], off offset:16
	s_waitcnt vmcnt(8)
	v_pk_add_f32 v[174:175], v[174:175], v[190:191]
	v_pk_add_f32 v[176:177], v[176:177], v[192:193]
	v_pk_add_f32 v[178:179], v[178:179], v[194:195]
	v_pk_add_f32 v[180:181], v[180:181], v[196:197]
	v_pk_add_f32 v[182:183], v[182:183], v[198:199]
	v_pk_add_f32 v[184:185], v[184:185], v[200:201]
	v_pk_add_f32 v[186:187], v[186:187], v[204:205]
	v_pk_add_f32 v[188:189], v[188:189], v[206:207]
	s_waitcnt vmcnt(4)
	v_pk_add_f32 v[174:175], v[174:175], v[208:209]
	v_pk_add_f32 v[176:177], v[176:177], v[210:211]
	v_pk_add_f32 v[178:179], v[178:179], v[212:213]
	v_pk_add_f32 v[180:181], v[180:181], v[214:215]
	v_pk_add_f32 v[182:183], v[182:183], v[216:217]
	v_pk_add_f32 v[184:185], v[184:185], v[218:219]
	v_pk_add_f32 v[186:187], v[186:187], v[220:221]
	v_pk_add_f32 v[188:189], v[188:189], v[222:223]
	s_waitcnt vmcnt(0)
	v_pk_fma_f32 v[60:61], v[174:175], v[224:225], v[60:61]
	v_pk_fma_f32 v[62:63], v[176:177], v[226:227], v[62:63]
	v_pk_fma_f32 v[58:59], v[178:179], v[228:229], v[58:59]
	v_pk_fma_f32 v[64:65], v[180:181], v[230:231], v[64:65]
	v_pk_fma_f32 v[54:55], v[182:183], v[238:239], v[54:55]
	v_pk_fma_f32 v[56:57], v[184:185], v[240:241], v[56:57]
	v_pk_fma_f32 v[32:33], v[186:187], v[242:243], v[32:33]
	v_pk_fma_f32 v[50:51], v[188:189], v[244:245], v[50:51]
